# K-loop v4: trailing barrier 4 MFMAs early with priority ladder
# baseline (speedup 1.0000x reference)
; #define PG8_STAGE(bufoff, gbase, voff) do { _Pragma("unroll") for (int _i = 0; _i < 2; ++_i) \
;         __builtin_amdgcn_global_load_lds((const unsigned*)((const char*)(gbase) + (voff)[_i]), (PG8_LAS unsigned*)(lds + (bufoff) + ldsw + _i * 8192), 16, 0, 0); } while (0)
; #define PG8_LDA(dst, b, h) do { _Pragma("unroll") for (int m = 0; m < 4; ++m) _Pragma("unroll") for (int k = 0; k < 2; ++k) dst[m][k] = *(const PG8_LAS bf16x8*)(lds + PG8_SA(b, h) + aoff + m * 2048 + k * 1024); } while (0)
; #define PG8_MMA(ai, bj, At, Bt) do { __builtin_amdgcn_s_setprio(1); _Pragma("unroll") for (int m = 0; m < 4; ++m) _Pragma("unroll") for (int n = 0; n < 2; ++n) _Pragma("unroll") for (int k = 0; k < 2; ++k) \
;         acc[ai][bj][m][n] = __builtin_amdgcn_mfma_f32_16x16x32_bf16(Bt[n][k], At[m][k], acc[ai][bj][m][n], 0, 0, 0); __builtin_amdgcn_s_setprio(0); } while (0)
; #define PG8_WAIT_L(n) asm volatile("s_waitcnt lgkmcnt(" #n ")" ::: "memory")
; #define PG8_WAIT_V8_UNLESS(flag) asm volatile("s_cmp_lg_i32 %0, 0\n\ts_cbranch_scc1 .Lpg8rx%=\n\ts_waitcnt vmcnt(8)\n.Lpg8rx%=:" :: "s"(__builtin_amdgcn_readfirstlane(flag)) : "scc", "memory")
; #define PG8_BAR __builtin_amdgcn_s_barrier()
; #define PG8_SCHED __builtin_amdgcn_sched_barrier(0)
; template <class Epi, class Sched, bool ALIGN_EPI = false, bool SP2 = false>
; __device__ __forceinline__ void gemm_phase(PG8_LAS unsigned char* lds, const Gemm g, const Sched& S, const Epi& E) {
;     ...
;             PG8_WAIT_V8_UNLESS(rx); PG8_WAIT_L(0); PG8_BAR; PG8_MMA(0, 0, At, B0); PG8_MMA(0, 1, At, B1); PG8_BAR; PG8_SCHED;
;             PG8_STAGE(PG8_SB(0, 0), b2, voffB); PG8_STAGE(PG8_SB(0, 1), b2 + hstep, voffB); PG8_STAGE(PG8_SA(0, 0), a2, voffA); PG8_SCHED; PG8_LDA(At, 0, 1);
;             PG8_WAIT_V8_UNLESS(rx); PG8_WAIT_L(0); PG8_BAR; PG8_MMA(1, 0, At, B0); PG8_MMA(1, 1, At, B1); PG8_BAR; PG8_SCHED;
.Lpg8rx0:
	s_waitcnt lgkmcnt(0)
	s_setprio 2
	s_barrier
	v_mfma_f32_16x16x32_bf16 v[124:127], v[144:147], v[178:181], v[124:127]
	v_mfma_f32_16x16x32_bf16 v[120:123], v[152:155], v[178:181], v[120:123]
	v_mfma_f32_16x16x32_bf16 v[108:111], v[144:147], v[186:189], v[108:111]
	v_mfma_f32_16x16x32_bf16 v[104:107], v[152:155], v[186:189], v[104:107]
	v_mfma_f32_16x16x32_bf16 v[92:95], v[144:147], v[208:211], v[92:95]
	v_mfma_f32_16x16x32_bf16 v[88:91], v[152:155], v[208:211], v[88:91]
	v_mfma_f32_16x16x32_bf16 v[76:79], v[144:147], v[216:219], v[76:79]
	v_mfma_f32_16x16x32_bf16 v[72:75], v[152:155], v[216:219], v[72:75]
	v_mfma_f32_16x16x32_bf16 v[124:127], v[148:151], v[182:185], v[124:127]
	v_mfma_f32_16x16x32_bf16 v[120:123], v[156:159], v[182:185], v[120:123]
	v_mfma_f32_16x16x32_bf16 v[108:111], v[148:151], v[204:207], v[108:111]
	v_mfma_f32_16x16x32_bf16 v[104:107], v[156:159], v[204:207], v[104:107]
	v_mfma_f32_16x16x32_bf16 v[92:95], v[148:151], v[212:215], v[92:95]
	v_mfma_f32_16x16x32_bf16 v[88:91], v[156:159], v[212:215], v[88:91]
	v_mfma_f32_16x16x32_bf16 v[76:79], v[148:151], v[220:223], v[76:79]
	v_mfma_f32_16x16x32_bf16 v[72:75], v[156:159], v[220:223], v[72:75]
	v_mfma_f32_16x16x32_bf16 v[116:119], v[160:163], v[178:181], v[116:119]
	v_mfma_f32_16x16x32_bf16 v[112:115], v[168:171], v[178:181], v[112:115]
	v_mfma_f32_16x16x32_bf16 v[100:103], v[160:163], v[186:189], v[100:103]
	v_mfma_f32_16x16x32_bf16 v[96:99], v[168:171], v[186:189], v[96:99]
	v_mfma_f32_16x16x32_bf16 v[84:87], v[160:163], v[208:211], v[84:87]
	v_mfma_f32_16x16x32_bf16 v[80:83], v[168:171], v[208:211], v[80:83]
	v_mfma_f32_16x16x32_bf16 v[68:71], v[160:163], v[216:219], v[68:71]
	v_mfma_f32_16x16x32_bf16 v[64:67], v[168:171], v[216:219], v[64:67]
	v_mfma_f32_16x16x32_bf16 v[116:119], v[164:167], v[182:185], v[116:119]
	v_mfma_f32_16x16x32_bf16 v[112:115], v[174:177], v[182:185], v[112:115]
	v_mfma_f32_16x16x32_bf16 v[100:103], v[164:167], v[204:207], v[100:103]
	v_mfma_f32_16x16x32_bf16 v[96:99], v[174:177], v[204:207], v[96:99]
	s_setprio 3
	s_barrier
	v_mfma_f32_16x16x32_bf16 v[84:87], v[164:167], v[212:215], v[84:87]
	v_mfma_f32_16x16x32_bf16 v[80:83], v[174:177], v[212:215], v[80:83]
	v_mfma_f32_16x16x32_bf16 v[68:71], v[164:167], v[220:223], v[68:71]
	v_mfma_f32_16x16x32_bf16 v[64:67], v[174:177], v[220:223], v[64:67]
	s_setprio 0
	ds_read_b128 v[178:181], v173 offset:16384
	ds_read_b128 v[182:185], v173 offset:17408
	ds_read_b128 v[186:189], v173 offset:18432
	ds_read_b128 v[204:207], v173 offset:19456
	ds_read_b128 v[208:211], v173 offset:20480
	ds_read_b128 v[212:215], v173 offset:21504
	ds_read_b128 v[216:219], v173 offset:22528
	ds_read_b128 v[220:223], v173 offset:23552
	s_add_u32 s66, s28, 0x40000
	s_addc_u32 s67, s29, 0
	s_add_i32 m0, s61, s46
	s_nop 0
	global_load_lds_dwordx4 v134, s[28:29]
	s_add_i32 m0, m0, 0x2000
	s_nop 0
	global_load_lds_dwordx4 v138, s[28:29]
	s_add_i32 m0, s65, s46
	s_nop 0
	global_load_lds_dwordx4 v134, s[66:67]
	s_add_i32 m0, m0, 0x2000
	s_nop 0
	global_load_lds_dwordx4 v138, s[66:67]
	s_mov_b32 m0, s9
	s_nop 0
	global_load_lds_dwordx4 v132, s[30:31]
	s_mov_b32 m0, s51
	s_nop 0
	global_load_lds_dwordx4 v136, s[30:31]
	s_cmp_lg_i32 s70, 0
	s_cbranch_scc1 .Lpg8rx1
	s_waitcnt vmcnt(8)
.Lpg8rx1:
	s_waitcnt lgkmcnt(0)
	s_setprio 2
	s_barrier
	v_mfma_f32_16x16x32_bf16 v[60:63], v[144:147], v[178:181], v[60:63]
	v_mfma_f32_16x16x32_bf16 v[56:59], v[152:155], v[178:181], v[56:59]
	v_mfma_f32_16x16x32_bf16 v[44:47], v[144:147], v[186:189], v[44:47]
	v_mfma_f32_16x16x32_bf16 v[40:43], v[152:155], v[186:189], v[40:43]
	v_mfma_f32_16x16x32_bf16 v[28:31], v[144:147], v[208:211], v[28:31]
	v_mfma_f32_16x16x32_bf16 v[24:27], v[152:155], v[208:211], v[24:27]
	v_mfma_f32_16x16x32_bf16 v[12:15], v[144:147], v[216:219], v[12:15]
	v_mfma_f32_16x16x32_bf16 v[8:11], v[152:155], v[216:219], v[8:11]
	v_mfma_f32_16x16x32_bf16 v[60:63], v[148:151], v[182:185], v[60:63]
	v_mfma_f32_16x16x32_bf16 v[56:59], v[156:159], v[182:185], v[56:59]
	v_mfma_f32_16x16x32_bf16 v[44:47], v[148:151], v[204:207], v[44:47]
	v_mfma_f32_16x16x32_bf16 v[40:43], v[156:159], v[204:207], v[40:43]
	v_mfma_f32_16x16x32_bf16 v[28:31], v[148:151], v[212:215], v[28:31]
	v_mfma_f32_16x16x32_bf16 v[24:27], v[156:159], v[212:215], v[24:27]
	v_mfma_f32_16x16x32_bf16 v[12:15], v[148:151], v[220:223], v[12:15]
	v_mfma_f32_16x16x32_bf16 v[8:11], v[156:159], v[220:223], v[8:11]
	v_mfma_f32_16x16x32_bf16 v[52:55], v[160:163], v[178:181], v[52:55]
	v_mfma_f32_16x16x32_bf16 v[48:51], v[168:171], v[178:181], v[48:51]
	v_mfma_f32_16x16x32_bf16 v[36:39], v[160:163], v[186:189], v[36:39]
	v_mfma_f32_16x16x32_bf16 v[32:35], v[168:171], v[186:189], v[32:35]
	v_mfma_f32_16x16x32_bf16 v[20:23], v[160:163], v[208:211], v[20:23]
	v_mfma_f32_16x16x32_bf16 v[16:19], v[168:171], v[208:211], v[16:19]
	v_mfma_f32_16x16x32_bf16 v[4:7], v[160:163], v[216:219], v[4:7]
	v_mfma_f32_16x16x32_bf16 v[0:3], v[168:171], v[216:219], v[0:3]
	v_mfma_f32_16x16x32_bf16 v[52:55], v[164:167], v[182:185], v[52:55]
	v_mfma_f32_16x16x32_bf16 v[48:51], v[174:177], v[182:185], v[48:51]
	v_mfma_f32_16x16x32_bf16 v[36:39], v[164:167], v[204:207], v[36:39]
	v_mfma_f32_16x16x32_bf16 v[32:35], v[174:177], v[204:207], v[32:35]
	s_setprio 3
	s_barrier
; #define PG8_STAGE(bufoff, gbase, voff) do { _Pragma("unroll") for (int _i = 0; _i < 2; ++_i) \
;         __builtin_amdgcn_global_load_lds((const unsigned*)((const char*)(gbase) + (voff)[_i]), (PG8_LAS unsigned*)(lds + (bufoff) + ldsw + _i * 8192), 16, 0, 0); } while (0)
; #define PG8_LDA(dst, b, h) do { _Pragma("unroll") for (int m = 0; m < 4; ++m) _Pragma("unroll") for (int k = 0; k < 2; ++k) dst[m][k] = *(const PG8_LAS bf16x8*)(lds + PG8_SA(b, h) + aoff + m * 2048 + k * 1024); } while (0)
; #define PG8_LDB(dst, b, h) do { _Pragma("unroll") for (int n = 0; n < 2; ++n) _Pragma("unroll") for (int k = 0; k < 2; ++k) dst[n][k] = *(const PG8_LAS bf16x8*)(lds + PG8_SB(b, h) + boff + n * 2048 + k * 1024); } while (0)
; #define PG8_MMA(ai, bj, At, Bt) do { __builtin_amdgcn_s_setprio(1); _Pragma("unroll") for (int m = 0; m < 4; ++m) _Pragma("unroll") for (int n = 0; n < 2; ++n) _Pragma("unroll") for (int k = 0; k < 2; ++k) \
;         acc[ai][bj][m][n] = __builtin_amdgcn_mfma_f32_16x16x32_bf16(Bt[n][k], At[m][k], acc[ai][bj][m][n], 0, 0, 0); __builtin_amdgcn_s_setprio(0); } while (0)
; #define PG8_WAIT_V(n) asm volatile("s_waitcnt vmcnt(" #n ")" ::: "memory")
; #define PG8_WAIT_L(n) asm volatile("s_waitcnt lgkmcnt(" #n ")" ::: "memory")
; #define PG8_WAIT_V8_UNLESS(flag) asm volatile("s_cmp_lg_i32 %0, 0\n\ts_cbranch_scc1 .Lpg8rx%=\n\ts_waitcnt vmcnt(8)\n.Lpg8rx%=:" :: "s"(__builtin_amdgcn_readfirstlane(flag)) : "scc", "memory")
; #define PG8_BAR __builtin_amdgcn_s_barrier()
; #define PG8_SCHED __builtin_amdgcn_sched_barrier(0)
; template <class Epi, class Sched, bool ALIGN_EPI = false, bool SP2 = false>
; __device__ __forceinline__ void gemm_phase(PG8_LAS unsigned char* lds, const Gemm g, const Sched& S, const Epi& E) {
;     ...
;             PG8_WAIT_V8_UNLESS(rx); PG8_WAIT_L(0); PG8_BAR; PG8_MMA(1, 0, At, B0); PG8_MMA(1, 1, At, B1); PG8_BAR; PG8_SCHED;
;             PG8_STAGE(PG8_SA(0, 1), a2 + hstep, voffA); PG8_SCHED; PG8_LDB(B0, 1, 0); PG8_LDB(B1, 1, 1); PG8_SCHED; PG8_LDA(At, 1, 0);
;             PG8_WAIT_V(8); PG8_WAIT_L(0); PG8_BAR; PG8_MMA(0, 0, At, B0); PG8_MMA(0, 1, At, B1); PG8_BAR; PG8_SCHED;
	v_mfma_f32_16x16x32_bf16 v[20:23], v[164:167], v[212:215], v[20:23]
	v_mfma_f32_16x16x32_bf16 v[16:19], v[174:177], v[212:215], v[16:19]
	v_mfma_f32_16x16x32_bf16 v[4:7], v[164:167], v[220:223], v[4:7]
	v_mfma_f32_16x16x32_bf16 v[0:3], v[174:177], v[220:223], v[0:3]
	s_setprio 0
	s_mov_b64 s[98:99], s[30:31]
	s_add_u32 s100, s30, 0x40000
	s_addc_u32 s101, s31, 0
	s_add_i32 s30, 0, 0x18000
	s_add_i32 s31, 0, 0x1c000
	v_add_u32_e32 v156, s30, v172
	v_add_u32_e32 v174, s31, v172
	ds_read_b128 v[144:147], v156
	ds_read_b128 v[148:151], v156 offset:1024
	ds_read_b128 v[152:155], v156 offset:2048
	ds_read_b128 v[156:159], v156 offset:3072
	ds_read_b128 v[160:163], v174
	ds_read_b128 v[164:167], v174 offset:1024
	ds_read_b128 v[168:171], v174 offset:2048
	ds_read_b128 v[174:177], v174 offset:3072
	ds_read_b128 v[178:181], v173 offset:32768
	ds_read_b128 v[182:185], v173 offset:33792
	ds_read_b128 v[186:189], v173 offset:34816
	ds_read_b128 v[204:207], v173 offset:35840
	ds_read_b128 v[208:211], v173 offset:36864
	ds_read_b128 v[212:215], v173 offset:37888
	ds_read_b128 v[216:219], v173 offset:38912
	ds_read_b128 v[220:223], v173 offset:39936
	s_mov_b32 m0, s52
	s_nop 0
	global_load_lds_dwordx4 v132, s[100:101]
	s_mov_b32 m0, s53
	s_nop 0
	global_load_lds_dwordx4 v136, s[100:101]
	s_waitcnt vmcnt(8)
	s_waitcnt lgkmcnt(0)
	s_setprio 2
	s_barrier
	v_mfma_f32_16x16x32_bf16 v[124:127], v[144:147], v[178:181], v[124:127]
	v_mfma_f32_16x16x32_bf16 v[120:123], v[152:155], v[178:181], v[120:123]
	v_mfma_f32_16x16x32_bf16 v[108:111], v[144:147], v[186:189], v[108:111]
	v_mfma_f32_16x16x32_bf16 v[104:107], v[152:155], v[186:189], v[104:107]
	v_mfma_f32_16x16x32_bf16 v[92:95], v[144:147], v[208:211], v[92:95]
	v_mfma_f32_16x16x32_bf16 v[88:91], v[152:155], v[208:211], v[88:91]
	v_mfma_f32_16x16x32_bf16 v[76:79], v[144:147], v[216:219], v[76:79]
	v_mfma_f32_16x16x32_bf16 v[72:75], v[152:155], v[216:219], v[72:75]
	v_mfma_f32_16x16x32_bf16 v[124:127], v[148:151], v[182:185], v[124:127]
	v_mfma_f32_16x16x32_bf16 v[120:123], v[156:159], v[182:185], v[120:123]
	v_mfma_f32_16x16x32_bf16 v[108:111], v[148:151], v[204:207], v[108:111]
	v_mfma_f32_16x16x32_bf16 v[104:107], v[156:159], v[204:207], v[104:107]
	v_mfma_f32_16x16x32_bf16 v[92:95], v[148:151], v[212:215], v[92:95]
	v_mfma_f32_16x16x32_bf16 v[88:91], v[156:159], v[212:215], v[88:91]
	v_mfma_f32_16x16x32_bf16 v[76:79], v[148:151], v[220:223], v[76:79]
	v_mfma_f32_16x16x32_bf16 v[72:75], v[156:159], v[220:223], v[72:75]
	v_mfma_f32_16x16x32_bf16 v[116:119], v[160:163], v[178:181], v[116:119]
	v_mfma_f32_16x16x32_bf16 v[112:115], v[168:171], v[178:181], v[112:115]
	v_mfma_f32_16x16x32_bf16 v[100:103], v[160:163], v[186:189], v[100:103]
	v_mfma_f32_16x16x32_bf16 v[96:99], v[168:171], v[186:189], v[96:99]
	v_mfma_f32_16x16x32_bf16 v[84:87], v[160:163], v[208:211], v[84:87]
	v_mfma_f32_16x16x32_bf16 v[80:83], v[168:171], v[208:211], v[80:83]
	v_mfma_f32_16x16x32_bf16 v[68:71], v[160:163], v[216:219], v[68:71]
	v_mfma_f32_16x16x32_bf16 v[64:67], v[168:171], v[216:219], v[64:67]
	v_mfma_f32_16x16x32_bf16 v[116:119], v[164:167], v[182:185], v[116:119]
	v_mfma_f32_16x16x32_bf16 v[112:115], v[174:177], v[182:185], v[112:115]
	v_mfma_f32_16x16x32_bf16 v[100:103], v[164:167], v[204:207], v[100:103]
	v_mfma_f32_16x16x32_bf16 v[96:99], v[174:177], v[204:207], v[96:99]
	s_setprio 3
	s_barrier
; #define PG8_STAGE(bufoff, gbase, voff) do { _Pragma("unroll") for (int _i = 0; _i < 2; ++_i) \
;         __builtin_amdgcn_global_load_lds((const unsigned*)((const char*)(gbase) + (voff)[_i]), (PG8_LAS unsigned*)(lds + (bufoff) + ldsw + _i * 8192), 16, 0, 0); } while (0)
; #define PG8_LDA(dst, b, h) do { _Pragma("unroll") for (int m = 0; m < 4; ++m) _Pragma("unroll") for (int k = 0; k < 2; ++k) dst[m][k] = *(const PG8_LAS bf16x8*)(lds + PG8_SA(b, h) + aoff + m * 2048 + k * 1024); } while (0)
; #define PG8_MMA(ai, bj, At, Bt) do { __builtin_amdgcn_s_setprio(1); _Pragma("unroll") for (int m = 0; m < 4; ++m) _Pragma("unroll") for (int n = 0; n < 2; ++n) _Pragma("unroll") for (int k = 0; k < 2; ++k) \
;         acc[ai][bj][m][n] = __builtin_amdgcn_mfma_f32_16x16x32_bf16(Bt[n][k], At[m][k], acc[ai][bj][m][n], 0, 0, 0); __builtin_amdgcn_s_setprio(0); } while (0)
; #define PG8_WAIT_V(n) asm volatile("s_waitcnt vmcnt(" #n ")" ::: "memory")
; #define PG8_WAIT_L(n) asm volatile("s_waitcnt lgkmcnt(" #n ")" ::: "memory")
; #define PG8_BAR __builtin_amdgcn_s_barrier()
; #define PG8_SCHED __builtin_amdgcn_sched_barrier(0)
; template <class Epi, class Sched, bool ALIGN_EPI = false, bool SP2 = false>
; __device__ __forceinline__ void gemm_phase(PG8_LAS unsigned char* lds, const Gemm g, const Sched& S, const Epi& E) {
;     ...
;             PG8_WAIT_V(8); PG8_WAIT_L(0); PG8_BAR; PG8_MMA(0, 0, At, B0); PG8_MMA(0, 1, At, B1); PG8_BAR; PG8_SCHED;
;             PG8_STAGE(PG8_SB(1, 0), b3, voffB); PG8_STAGE(PG8_SB(1, 1), b3 + hstep, voffB); PG8_STAGE(PG8_SA(1, 0), a3, voffA); PG8_SCHED; PG8_LDA(At, 1, 1);
;             PG8_WAIT_V(8); PG8_WAIT_L(0); PG8_BAR; PG8_MMA(1, 0, At, B0); PG8_MMA(1, 1, At, B1); PG8_BAR; PG8_SCHED;
	v_mfma_f32_16x16x32_bf16 v[84:87], v[164:167], v[212:215], v[84:87]
	v_mfma_f32_16x16x32_bf16 v[80:83], v[174:177], v[212:215], v[80:83]
	v_mfma_f32_16x16x32_bf16 v[68:71], v[164:167], v[220:223], v[68:71]
	v_mfma_f32_16x16x32_bf16 v[64:67], v[174:177], v[220:223], v[64:67]
	s_setprio 0
	ds_read_b128 v[178:181], v173 offset:49152
	ds_read_b128 v[182:185], v173 offset:50176
	ds_read_b128 v[186:189], v173 offset:51200
	ds_read_b128 v[204:207], v173 offset:52224
	ds_read_b128 v[208:211], v173 offset:53248
	ds_read_b128 v[212:215], v173 offset:54272
	ds_read_b128 v[216:219], v173 offset:55296
	ds_read_b128 v[220:223], v173 offset:56320
	s_add_u32 s100, s28, 0x80
	s_addc_u32 s101, s29, 0
	s_add_u32 s28, s28, 0x40080
	s_addc_u32 s29, s29, 0
	s_add_u32 s98, s98, 0x80
	s_addc_u32 s99, s99, 0
	s_add_i32 m0, s30, s46
	s_nop 0
	global_load_lds_dwordx4 v134, s[100:101]
	s_add_i32 m0, m0, 0x2000
	s_nop 0
	global_load_lds_dwordx4 v138, s[100:101]
	s_add_i32 m0, s31, s46
	s_nop 0
	global_load_lds_dwordx4 v134, s[28:29]
	s_add_i32 m0, m0, 0x2000
	s_nop 0
	global_load_lds_dwordx4 v138, s[28:29]
	s_mov_b32 m0, s54
	s_nop 0
	global_load_lds_dwordx4 v132, s[98:99]
	s_mov_b32 m0, s55
	s_nop 0
	global_load_lds_dwordx4 v136, s[98:99]
	s_waitcnt vmcnt(8)
	s_waitcnt lgkmcnt(0)
	s_setprio 2
	s_barrier
	v_mfma_f32_16x16x32_bf16 v[60:63], v[144:147], v[178:181], v[60:63]
	v_mfma_f32_16x16x32_bf16 v[56:59], v[152:155], v[178:181], v[56:59]
	v_mfma_f32_16x16x32_bf16 v[44:47], v[144:147], v[186:189], v[44:47]
	v_mfma_f32_16x16x32_bf16 v[40:43], v[152:155], v[186:189], v[40:43]
	v_mfma_f32_16x16x32_bf16 v[28:31], v[144:147], v[208:211], v[28:31]
	v_mfma_f32_16x16x32_bf16 v[24:27], v[152:155], v[208:211], v[24:27]
	v_mfma_f32_16x16x32_bf16 v[12:15], v[144:147], v[216:219], v[12:15]
	v_mfma_f32_16x16x32_bf16 v[8:11], v[152:155], v[216:219], v[8:11]
	v_mfma_f32_16x16x32_bf16 v[60:63], v[148:151], v[182:185], v[60:63]
	v_mfma_f32_16x16x32_bf16 v[56:59], v[156:159], v[182:185], v[56:59]
	v_mfma_f32_16x16x32_bf16 v[44:47], v[148:151], v[204:207], v[44:47]
	v_mfma_f32_16x16x32_bf16 v[40:43], v[156:159], v[204:207], v[40:43]
	v_mfma_f32_16x16x32_bf16 v[28:31], v[148:151], v[212:215], v[28:31]
	v_mfma_f32_16x16x32_bf16 v[24:27], v[156:159], v[212:215], v[24:27]
	v_mfma_f32_16x16x32_bf16 v[12:15], v[148:151], v[220:223], v[12:15]
	v_mfma_f32_16x16x32_bf16 v[8:11], v[156:159], v[220:223], v[8:11]
	v_mfma_f32_16x16x32_bf16 v[52:55], v[160:163], v[178:181], v[52:55]
	v_mfma_f32_16x16x32_bf16 v[48:51], v[168:171], v[178:181], v[48:51]
	v_mfma_f32_16x16x32_bf16 v[36:39], v[160:163], v[186:189], v[36:39]
	v_mfma_f32_16x16x32_bf16 v[32:35], v[168:171], v[186:189], v[32:35]
	v_mfma_f32_16x16x32_bf16 v[20:23], v[160:163], v[208:211], v[20:23]
	v_mfma_f32_16x16x32_bf16 v[16:19], v[168:171], v[208:211], v[16:19]
	v_mfma_f32_16x16x32_bf16 v[4:7], v[160:163], v[216:219], v[4:7]
	v_mfma_f32_16x16x32_bf16 v[0:3], v[168:171], v[216:219], v[0:3]
	v_mfma_f32_16x16x32_bf16 v[52:55], v[164:167], v[182:185], v[52:55]
	v_mfma_f32_16x16x32_bf16 v[48:51], v[174:177], v[182:185], v[48:51]
	v_mfma_f32_16x16x32_bf16 v[36:39], v[164:167], v[204:207], v[36:39]
	v_mfma_f32_16x16x32_bf16 v[32:35], v[174:177], v[204:207], v[32:35]
	s_setprio 3
	s_barrier
	v_mfma_f32_16x16x32_bf16 v[20:23], v[164:167], v[212:215], v[20:23]
	v_mfma_f32_16x16x32_bf16 v[16:19], v[174:177], v[212:215], v[16:19]
	v_mfma_f32_16x16x32_bf16 v[4:7], v[164:167], v[220:223], v[4:7]
	v_mfma_f32_16x16x32_bf16 v[0:3], v[174:177], v[220:223], v[0:3]
	s_setprio 0
	s_add_i32 s60, s60, 2
	s_add_u32 vcc_lo, vcc_lo, 0x100
	s_addc_u32 vcc_hi, vcc_hi, 0
	s_cmp_gt_u32 s60, 13
	s_cbranch_scc0 .LBB0_148
	s_and_b64 vcc, exec, s[62:63]
	s_cbranch_vccz .LBB0_151
	s_barrier

; #define PG8_STAGE(bufoff, gbase, voff) do { _Pragma("unroll") for (int _i = 0; _i < 2; ++_i) \
;         __builtin_amdgcn_global_load_lds((const unsigned*)((const char*)(gbase) + (voff)[_i]), (PG8_LAS unsigned*)(lds + (bufoff) + ldsw + _i * 8192), 16, 0, 0); } while (0)
; #define PG8_LDA(dst, b, h) do { _Pragma("unroll") for (int m = 0; m < 4; ++m) _Pragma("unroll") for (int k = 0; k < 2; ++k) dst[m][k] = *(const PG8_LAS bf16x8*)(lds + PG8_SA(b, h) + aoff + m * 2048 + k * 1024); } while (0)
; #define PG8_MMA(ai, bj, At, Bt) do { __builtin_amdgcn_s_setprio(1); _Pragma("unroll") for (int m = 0; m < 4; ++m) _Pragma("unroll") for (int n = 0; n < 2; ++n) _Pragma("unroll") for (int k = 0; k < 2; ++k) \
;         acc[ai][bj][m][n] = __builtin_amdgcn_mfma_f32_16x16x32_bf16(Bt[n][k], At[m][k], acc[ai][bj][m][n], 0, 0, 0); __builtin_amdgcn_s_setprio(0); } while (0)
; #define PG8_WAIT_L(n) asm volatile("s_waitcnt lgkmcnt(" #n ")" ::: "memory")
; #define PG8_WAIT_V8_UNLESS(flag) asm volatile("s_cmp_lg_i32 %0, 0\n\ts_cbranch_scc1 .Lpg8rx%=\n\ts_waitcnt vmcnt(8)\n.Lpg8rx%=:" :: "s"(__builtin_amdgcn_readfirstlane(flag)) : "scc", "memory")
; #define PG8_BAR __builtin_amdgcn_s_barrier()
; #define PG8_SCHED __builtin_amdgcn_sched_barrier(0)
; template <class Epi, class Sched, bool ALIGN_EPI = false, bool SP2 = false>
; __device__ __forceinline__ void gemm_phase(PG8_LAS unsigned char* lds, const Gemm g, const Sched& S, const Epi& E) {
;     ...
;             PG8_WAIT_V8_UNLESS(rx); PG8_WAIT_L(0); PG8_BAR; PG8_MMA(0, 0, At, B0); PG8_MMA(0, 1, At, B1); PG8_BAR; PG8_SCHED;
;             PG8_STAGE(PG8_SB(0, 0), b2, voffB); PG8_STAGE(PG8_SB(0, 1), b2 + hstep, voffB); PG8_STAGE(PG8_SA(0, 0), a2, voffA); PG8_SCHED; PG8_LDA(At, 0, 1);
;             PG8_WAIT_V8_UNLESS(rx); PG8_WAIT_L(0); PG8_BAR; PG8_MMA(1, 0, At, B0); PG8_MMA(1, 1, At, B1); PG8_BAR; PG8_SCHED;
.Lpg8rx2:
	s_waitcnt lgkmcnt(0)
	s_setprio 2
	s_barrier
	v_mfma_f32_16x16x32_bf16 v[152:155], v[120:123], v[164:167], v[152:155]
	v_mfma_f32_16x16x32_bf16 v[148:151], v[132:135], v[164:167], v[148:151]
	v_mfma_f32_16x16x32_bf16 v[108:111], v[120:123], v[172:175], v[108:111]
	v_mfma_f32_16x16x32_bf16 v[104:107], v[132:135], v[172:175], v[104:107]
	v_mfma_f32_16x16x32_bf16 v[92:95], v[120:123], v[180:183], v[92:95]
	v_mfma_f32_16x16x32_bf16 v[88:91], v[132:135], v[180:183], v[88:91]
	v_mfma_f32_16x16x32_bf16 v[76:79], v[120:123], v[188:191], v[76:79]
	v_mfma_f32_16x16x32_bf16 v[72:75], v[132:135], v[188:191], v[72:75]
	v_mfma_f32_16x16x32_bf16 v[152:155], v[128:131], v[168:171], v[152:155]
	v_mfma_f32_16x16x32_bf16 v[148:151], v[136:139], v[168:171], v[148:151]
	v_mfma_f32_16x16x32_bf16 v[108:111], v[128:131], v[176:179], v[108:111]
	v_mfma_f32_16x16x32_bf16 v[104:107], v[136:139], v[176:179], v[104:107]
	v_mfma_f32_16x16x32_bf16 v[92:95], v[128:131], v[184:187], v[92:95]
	v_mfma_f32_16x16x32_bf16 v[88:91], v[136:139], v[184:187], v[88:91]
	v_mfma_f32_16x16x32_bf16 v[76:79], v[128:131], v[214:217], v[76:79]
	v_mfma_f32_16x16x32_bf16 v[72:75], v[136:139], v[214:217], v[72:75]
	v_mfma_f32_16x16x32_bf16 v[124:127], v[140:143], v[164:167], v[124:127]
	v_mfma_f32_16x16x32_bf16 v[112:115], v[156:159], v[164:167], v[112:115]
	v_mfma_f32_16x16x32_bf16 v[100:103], v[140:143], v[172:175], v[100:103]
	v_mfma_f32_16x16x32_bf16 v[96:99], v[156:159], v[172:175], v[96:99]
	v_mfma_f32_16x16x32_bf16 v[84:87], v[140:143], v[180:183], v[84:87]
	v_mfma_f32_16x16x32_bf16 v[80:83], v[156:159], v[180:183], v[80:83]
	v_mfma_f32_16x16x32_bf16 v[68:71], v[140:143], v[188:191], v[68:71]
	v_mfma_f32_16x16x32_bf16 v[64:67], v[156:159], v[188:191], v[64:67]
	v_mfma_f32_16x16x32_bf16 v[124:127], v[144:147], v[168:171], v[124:127]
	v_mfma_f32_16x16x32_bf16 v[112:115], v[160:163], v[168:171], v[112:115]
	v_mfma_f32_16x16x32_bf16 v[100:103], v[144:147], v[176:179], v[100:103]
	v_mfma_f32_16x16x32_bf16 v[96:99], v[160:163], v[176:179], v[96:99]
	s_setprio 3
	s_barrier
	v_mfma_f32_16x16x32_bf16 v[84:87], v[144:147], v[184:187], v[84:87]
	v_mfma_f32_16x16x32_bf16 v[80:83], v[160:163], v[184:187], v[80:83]
	v_mfma_f32_16x16x32_bf16 v[68:71], v[144:147], v[214:217], v[68:71]
	v_mfma_f32_16x16x32_bf16 v[64:67], v[160:163], v[214:217], v[64:67]
	s_setprio 0
	ds_read_b128 v[164:167], v248 offset:16384
	ds_read_b128 v[168:171], v248 offset:17408
	ds_read_b128 v[172:175], v248 offset:18432
	ds_read_b128 v[176:179], v248 offset:19456
	ds_read_b128 v[180:183], v248 offset:20480
	ds_read_b128 v[184:187], v248 offset:21504
	ds_read_b128 v[188:191], v248 offset:22528
	ds_read_b128 v[214:217], v248 offset:23552
	s_add_u32 s60, s28, 0x40000
	s_addc_u32 s61, s29, 0
	s_add_i32 m0, s59, s39
	s_nop 0
	global_load_lds_dwordx4 v194, s[28:29]
	s_add_i32 m0, m0, 0x2000
	s_nop 0
	global_load_lds_dwordx4 v208, s[28:29]
	s_add_i32 m0, s65, s39
	s_nop 0
	global_load_lds_dwordx4 v194, s[60:61]
	s_add_i32 m0, m0, 0x2000
	s_nop 0
	global_load_lds_dwordx4 v208, s[60:61]
	s_mov_b32 m0, s41
	s_nop 0
	global_load_lds_dwordx4 v204, s[30:31]
	s_mov_b32 m0, s44
	s_nop 0
	global_load_lds_dwordx4 v206, s[30:31]
	s_cmp_lg_i32 s66, 0
	s_cbranch_scc1 .Lpg8rx3
	s_waitcnt vmcnt(8)
.Lpg8rx3:
	s_waitcnt lgkmcnt(0)
	s_setprio 2
	s_barrier
	v_mfma_f32_16x16x32_bf16 v[60:63], v[120:123], v[164:167], v[60:63]
	v_mfma_f32_16x16x32_bf16 v[56:59], v[132:135], v[164:167], v[56:59]
	v_mfma_f32_16x16x32_bf16 v[44:47], v[120:123], v[172:175], v[44:47]
	v_mfma_f32_16x16x32_bf16 v[40:43], v[132:135], v[172:175], v[40:43]
	v_mfma_f32_16x16x32_bf16 v[28:31], v[120:123], v[180:183], v[28:31]
	v_mfma_f32_16x16x32_bf16 v[24:27], v[132:135], v[180:183], v[24:27]
	v_mfma_f32_16x16x32_bf16 v[12:15], v[120:123], v[188:191], v[12:15]
	v_mfma_f32_16x16x32_bf16 v[8:11], v[132:135], v[188:191], v[8:11]
	v_mfma_f32_16x16x32_bf16 v[60:63], v[128:131], v[168:171], v[60:63]
	v_mfma_f32_16x16x32_bf16 v[56:59], v[136:139], v[168:171], v[56:59]
	v_mfma_f32_16x16x32_bf16 v[44:47], v[128:131], v[176:179], v[44:47]
	v_mfma_f32_16x16x32_bf16 v[40:43], v[136:139], v[176:179], v[40:43]
	v_mfma_f32_16x16x32_bf16 v[28:31], v[128:131], v[184:187], v[28:31]
	v_mfma_f32_16x16x32_bf16 v[24:27], v[136:139], v[184:187], v[24:27]
	v_mfma_f32_16x16x32_bf16 v[12:15], v[128:131], v[214:217], v[12:15]
	v_mfma_f32_16x16x32_bf16 v[8:11], v[136:139], v[214:217], v[8:11]
	v_mfma_f32_16x16x32_bf16 v[52:55], v[140:143], v[164:167], v[52:55]
	v_mfma_f32_16x16x32_bf16 v[48:51], v[156:159], v[164:167], v[48:51]
	v_mfma_f32_16x16x32_bf16 v[36:39], v[140:143], v[172:175], v[36:39]
	v_mfma_f32_16x16x32_bf16 v[32:35], v[156:159], v[172:175], v[32:35]
	v_mfma_f32_16x16x32_bf16 v[20:23], v[140:143], v[180:183], v[20:23]
	v_mfma_f32_16x16x32_bf16 v[16:19], v[156:159], v[180:183], v[16:19]
	v_mfma_f32_16x16x32_bf16 v[4:7], v[140:143], v[188:191], v[4:7]
	v_mfma_f32_16x16x32_bf16 v[0:3], v[156:159], v[188:191], v[0:3]
	v_mfma_f32_16x16x32_bf16 v[52:55], v[144:147], v[168:171], v[52:55]
	v_mfma_f32_16x16x32_bf16 v[48:51], v[160:163], v[168:171], v[48:51]
	v_mfma_f32_16x16x32_bf16 v[36:39], v[144:147], v[176:179], v[36:39]
	v_mfma_f32_16x16x32_bf16 v[32:35], v[160:163], v[176:179], v[32:35]
	s_setprio 3
	s_barrier
; #define PG8_STAGE(bufoff, gbase, voff) do { _Pragma("unroll") for (int _i = 0; _i < 2; ++_i) \
;         __builtin_amdgcn_global_load_lds((const unsigned*)((const char*)(gbase) + (voff)[_i]), (PG8_LAS unsigned*)(lds + (bufoff) + ldsw + _i * 8192), 16, 0, 0); } while (0)
; #define PG8_LDA(dst, b, h) do { _Pragma("unroll") for (int m = 0; m < 4; ++m) _Pragma("unroll") for (int k = 0; k < 2; ++k) dst[m][k] = *(const PG8_LAS bf16x8*)(lds + PG8_SA(b, h) + aoff + m * 2048 + k * 1024); } while (0)
; #define PG8_LDB(dst, b, h) do { _Pragma("unroll") for (int n = 0; n < 2; ++n) _Pragma("unroll") for (int k = 0; k < 2; ++k) dst[n][k] = *(const PG8_LAS bf16x8*)(lds + PG8_SB(b, h) + boff + n * 2048 + k * 1024); } while (0)
; #define PG8_MMA(ai, bj, At, Bt) do { __builtin_amdgcn_s_setprio(1); _Pragma("unroll") for (int m = 0; m < 4; ++m) _Pragma("unroll") for (int n = 0; n < 2; ++n) _Pragma("unroll") for (int k = 0; k < 2; ++k) \
;         acc[ai][bj][m][n] = __builtin_amdgcn_mfma_f32_16x16x32_bf16(Bt[n][k], At[m][k], acc[ai][bj][m][n], 0, 0, 0); __builtin_amdgcn_s_setprio(0); } while (0)
; #define PG8_WAIT_V(n) asm volatile("s_waitcnt vmcnt(" #n ")" ::: "memory")
; #define PG8_WAIT_L(n) asm volatile("s_waitcnt lgkmcnt(" #n ")" ::: "memory")
; #define PG8_WAIT_V8_UNLESS(flag) asm volatile("s_cmp_lg_i32 %0, 0\n\ts_cbranch_scc1 .Lpg8rx%=\n\ts_waitcnt vmcnt(8)\n.Lpg8rx%=:" :: "s"(__builtin_amdgcn_readfirstlane(flag)) : "scc", "memory")
; #define PG8_BAR __builtin_amdgcn_s_barrier()
; #define PG8_SCHED __builtin_amdgcn_sched_barrier(0)
; template <class Epi, class Sched, bool ALIGN_EPI = false, bool SP2 = false>
; __device__ __forceinline__ void gemm_phase(PG8_LAS unsigned char* lds, const Gemm g, const Sched& S, const Epi& E) {
;     ...
;             PG8_WAIT_V8_UNLESS(rx); PG8_WAIT_L(0); PG8_BAR; PG8_MMA(1, 0, At, B0); PG8_MMA(1, 1, At, B1); PG8_BAR; PG8_SCHED;
;             PG8_STAGE(PG8_SA(0, 1), a2 + hstep, voffA); PG8_SCHED; PG8_LDB(B0, 1, 0); PG8_LDB(B1, 1, 1); PG8_SCHED; PG8_LDA(At, 1, 0);
;             PG8_WAIT_V(8); PG8_WAIT_L(0); PG8_BAR; PG8_MMA(0, 0, At, B0); PG8_MMA(0, 1, At, B1); PG8_BAR; PG8_SCHED;
	v_mfma_f32_16x16x32_bf16 v[20:23], v[144:147], v[184:187], v[20:23]
	v_mfma_f32_16x16x32_bf16 v[16:19], v[160:163], v[184:187], v[16:19]
	v_mfma_f32_16x16x32_bf16 v[4:7], v[144:147], v[214:217], v[4:7]
	v_mfma_f32_16x16x32_bf16 v[0:3], v[160:163], v[214:217], v[0:3]
	s_setprio 0
	s_mov_b64 s[98:99], s[30:31]
	s_add_u32 s100, s30, 0x40000
	s_addc_u32 s101, s31, 0
	s_add_i32 s30, 0, 0x18000
	s_add_i32 s31, 0, 0x1c000
	v_add_u32_e32 v136, s30, v247
	v_add_u32_e32 v160, s31, v247
	ds_read_b128 v[120:123], v136
	ds_read_b128 v[128:131], v136 offset:1024
	ds_read_b128 v[132:135], v136 offset:2048
	ds_read_b128 v[136:139], v136 offset:3072
	ds_read_b128 v[140:143], v160
	ds_read_b128 v[144:147], v160 offset:1024
	ds_read_b128 v[156:159], v160 offset:2048
	ds_read_b128 v[160:163], v160 offset:3072
	ds_read_b128 v[164:167], v248 offset:32768
	ds_read_b128 v[168:171], v248 offset:33792
	ds_read_b128 v[172:175], v248 offset:34816
	ds_read_b128 v[176:179], v248 offset:35840
	ds_read_b128 v[180:183], v248 offset:36864
	ds_read_b128 v[184:187], v248 offset:37888
	ds_read_b128 v[188:191], v248 offset:38912
	ds_read_b128 v[214:217], v248 offset:39936
	s_mov_b32 m0, s46
	s_nop 0
	global_load_lds_dwordx4 v204, s[100:101]
	s_mov_b32 m0, s48
	s_nop 0
	global_load_lds_dwordx4 v206, s[100:101]
	s_waitcnt vmcnt(8)
	s_waitcnt lgkmcnt(0)
	s_setprio 2
	s_barrier
	v_mfma_f32_16x16x32_bf16 v[152:155], v[120:123], v[164:167], v[152:155]
	v_mfma_f32_16x16x32_bf16 v[148:151], v[132:135], v[164:167], v[148:151]
	v_mfma_f32_16x16x32_bf16 v[108:111], v[120:123], v[172:175], v[108:111]
	v_mfma_f32_16x16x32_bf16 v[104:107], v[132:135], v[172:175], v[104:107]
	v_mfma_f32_16x16x32_bf16 v[92:95], v[120:123], v[180:183], v[92:95]
	v_mfma_f32_16x16x32_bf16 v[88:91], v[132:135], v[180:183], v[88:91]
	v_mfma_f32_16x16x32_bf16 v[76:79], v[120:123], v[188:191], v[76:79]
	v_mfma_f32_16x16x32_bf16 v[72:75], v[132:135], v[188:191], v[72:75]
	v_mfma_f32_16x16x32_bf16 v[152:155], v[128:131], v[168:171], v[152:155]
	v_mfma_f32_16x16x32_bf16 v[148:151], v[136:139], v[168:171], v[148:151]
	v_mfma_f32_16x16x32_bf16 v[108:111], v[128:131], v[176:179], v[108:111]
	v_mfma_f32_16x16x32_bf16 v[104:107], v[136:139], v[176:179], v[104:107]
	v_mfma_f32_16x16x32_bf16 v[92:95], v[128:131], v[184:187], v[92:95]
	v_mfma_f32_16x16x32_bf16 v[88:91], v[136:139], v[184:187], v[88:91]
	v_mfma_f32_16x16x32_bf16 v[76:79], v[128:131], v[214:217], v[76:79]
	v_mfma_f32_16x16x32_bf16 v[72:75], v[136:139], v[214:217], v[72:75]
	v_mfma_f32_16x16x32_bf16 v[124:127], v[140:143], v[164:167], v[124:127]
	v_mfma_f32_16x16x32_bf16 v[112:115], v[156:159], v[164:167], v[112:115]
	v_mfma_f32_16x16x32_bf16 v[100:103], v[140:143], v[172:175], v[100:103]
	v_mfma_f32_16x16x32_bf16 v[96:99], v[156:159], v[172:175], v[96:99]
	v_mfma_f32_16x16x32_bf16 v[84:87], v[140:143], v[180:183], v[84:87]
	v_mfma_f32_16x16x32_bf16 v[80:83], v[156:159], v[180:183], v[80:83]
	v_mfma_f32_16x16x32_bf16 v[68:71], v[140:143], v[188:191], v[68:71]
	v_mfma_f32_16x16x32_bf16 v[64:67], v[156:159], v[188:191], v[64:67]
	v_mfma_f32_16x16x32_bf16 v[124:127], v[144:147], v[168:171], v[124:127]
	v_mfma_f32_16x16x32_bf16 v[112:115], v[160:163], v[168:171], v[112:115]
	v_mfma_f32_16x16x32_bf16 v[100:103], v[144:147], v[176:179], v[100:103]
	v_mfma_f32_16x16x32_bf16 v[96:99], v[160:163], v[176:179], v[96:99]
	s_setprio 3
	s_barrier
; #define PG8_STAGE(bufoff, gbase, voff) do { _Pragma("unroll") for (int _i = 0; _i < 2; ++_i) \
;         __builtin_amdgcn_global_load_lds((const unsigned*)((const char*)(gbase) + (voff)[_i]), (PG8_LAS unsigned*)(lds + (bufoff) + ldsw + _i * 8192), 16, 0, 0); } while (0)
; #define PG8_LDA(dst, b, h) do { _Pragma("unroll") for (int m = 0; m < 4; ++m) _Pragma("unroll") for (int k = 0; k < 2; ++k) dst[m][k] = *(const PG8_LAS bf16x8*)(lds + PG8_SA(b, h) + aoff + m * 2048 + k * 1024); } while (0)
; #define PG8_MMA(ai, bj, At, Bt) do { __builtin_amdgcn_s_setprio(1); _Pragma("unroll") for (int m = 0; m < 4; ++m) _Pragma("unroll") for (int n = 0; n < 2; ++n) _Pragma("unroll") for (int k = 0; k < 2; ++k) \
;         acc[ai][bj][m][n] = __builtin_amdgcn_mfma_f32_16x16x32_bf16(Bt[n][k], At[m][k], acc[ai][bj][m][n], 0, 0, 0); __builtin_amdgcn_s_setprio(0); } while (0)
; #define PG8_WAIT_V(n) asm volatile("s_waitcnt vmcnt(" #n ")" ::: "memory")
; #define PG8_WAIT_L(n) asm volatile("s_waitcnt lgkmcnt(" #n ")" ::: "memory")
; #define PG8_BAR __builtin_amdgcn_s_barrier()
; #define PG8_SCHED __builtin_amdgcn_sched_barrier(0)
; template <class Epi, class Sched, bool ALIGN_EPI = false, bool SP2 = false>
; __device__ __forceinline__ void gemm_phase(PG8_LAS unsigned char* lds, const Gemm g, const Sched& S, const Epi& E) {
;     ...
;             PG8_WAIT_V(8); PG8_WAIT_L(0); PG8_BAR; PG8_MMA(0, 0, At, B0); PG8_MMA(0, 1, At, B1); PG8_BAR; PG8_SCHED;
;             PG8_STAGE(PG8_SB(1, 0), b3, voffB); PG8_STAGE(PG8_SB(1, 1), b3 + hstep, voffB); PG8_STAGE(PG8_SA(1, 0), a3, voffA); PG8_SCHED; PG8_LDA(At, 1, 1);
;             PG8_WAIT_V(8); PG8_WAIT_L(0); PG8_BAR; PG8_MMA(1, 0, At, B0); PG8_MMA(1, 1, At, B1); PG8_BAR; PG8_SCHED;
	v_mfma_f32_16x16x32_bf16 v[84:87], v[144:147], v[184:187], v[84:87]
	v_mfma_f32_16x16x32_bf16 v[80:83], v[160:163], v[184:187], v[80:83]
	v_mfma_f32_16x16x32_bf16 v[68:71], v[144:147], v[214:217], v[68:71]
	v_mfma_f32_16x16x32_bf16 v[64:67], v[160:163], v[214:217], v[64:67]
	s_setprio 0
	ds_read_b128 v[164:167], v248 offset:49152
	ds_read_b128 v[168:171], v248 offset:50176
	ds_read_b128 v[172:175], v248 offset:51200
	ds_read_b128 v[176:179], v248 offset:52224
	ds_read_b128 v[180:183], v248 offset:53248
	ds_read_b128 v[184:187], v248 offset:54272
	ds_read_b128 v[188:191], v248 offset:55296
	ds_read_b128 v[214:217], v248 offset:56320
	s_add_u32 s100, s28, 0x80
	s_addc_u32 s101, s29, 0
	s_add_u32 s28, s28, 0x40080
	s_addc_u32 s29, s29, 0
	s_add_u32 s98, s98, 0x80
	s_addc_u32 s99, s99, 0
	s_add_i32 m0, s30, s39
	s_nop 0
	global_load_lds_dwordx4 v194, s[100:101]
	s_add_i32 m0, m0, 0x2000
	s_nop 0
	global_load_lds_dwordx4 v208, s[100:101]
	s_add_i32 m0, s31, s39
	s_nop 0
	global_load_lds_dwordx4 v194, s[28:29]
	s_add_i32 m0, m0, 0x2000
	s_nop 0
	global_load_lds_dwordx4 v208, s[28:29]
	s_mov_b32 m0, s50
	s_nop 0
	global_load_lds_dwordx4 v204, s[98:99]
	s_mov_b32 m0, s51
	s_nop 0
	global_load_lds_dwordx4 v206, s[98:99]
	s_waitcnt vmcnt(8)
	s_waitcnt lgkmcnt(0)
	s_setprio 2
	s_barrier
	v_mfma_f32_16x16x32_bf16 v[60:63], v[120:123], v[164:167], v[60:63]
	v_mfma_f32_16x16x32_bf16 v[56:59], v[132:135], v[164:167], v[56:59]
	v_mfma_f32_16x16x32_bf16 v[44:47], v[120:123], v[172:175], v[44:47]
	v_mfma_f32_16x16x32_bf16 v[40:43], v[132:135], v[172:175], v[40:43]
	v_mfma_f32_16x16x32_bf16 v[28:31], v[120:123], v[180:183], v[28:31]
	v_mfma_f32_16x16x32_bf16 v[24:27], v[132:135], v[180:183], v[24:27]
	v_mfma_f32_16x16x32_bf16 v[12:15], v[120:123], v[188:191], v[12:15]
	v_mfma_f32_16x16x32_bf16 v[8:11], v[132:135], v[188:191], v[8:11]
	v_mfma_f32_16x16x32_bf16 v[60:63], v[128:131], v[168:171], v[60:63]
	v_mfma_f32_16x16x32_bf16 v[56:59], v[136:139], v[168:171], v[56:59]
	v_mfma_f32_16x16x32_bf16 v[44:47], v[128:131], v[176:179], v[44:47]
	v_mfma_f32_16x16x32_bf16 v[40:43], v[136:139], v[176:179], v[40:43]
	v_mfma_f32_16x16x32_bf16 v[28:31], v[128:131], v[184:187], v[28:31]
	v_mfma_f32_16x16x32_bf16 v[24:27], v[136:139], v[184:187], v[24:27]
	v_mfma_f32_16x16x32_bf16 v[12:15], v[128:131], v[214:217], v[12:15]
	v_mfma_f32_16x16x32_bf16 v[8:11], v[136:139], v[214:217], v[8:11]
	v_mfma_f32_16x16x32_bf16 v[52:55], v[140:143], v[164:167], v[52:55]
	v_mfma_f32_16x16x32_bf16 v[48:51], v[156:159], v[164:167], v[48:51]
	v_mfma_f32_16x16x32_bf16 v[36:39], v[140:143], v[172:175], v[36:39]
	v_mfma_f32_16x16x32_bf16 v[32:35], v[156:159], v[172:175], v[32:35]
	v_mfma_f32_16x16x32_bf16 v[20:23], v[140:143], v[180:183], v[20:23]
	v_mfma_f32_16x16x32_bf16 v[16:19], v[156:159], v[180:183], v[16:19]
	v_mfma_f32_16x16x32_bf16 v[4:7], v[140:143], v[188:191], v[4:7]
	v_mfma_f32_16x16x32_bf16 v[0:3], v[156:159], v[188:191], v[0:3]
	v_mfma_f32_16x16x32_bf16 v[52:55], v[144:147], v[168:171], v[52:55]
	v_mfma_f32_16x16x32_bf16 v[48:51], v[160:163], v[168:171], v[48:51]
	v_mfma_f32_16x16x32_bf16 v[36:39], v[144:147], v[176:179], v[36:39]
	v_mfma_f32_16x16x32_bf16 v[32:35], v[160:163], v[176:179], v[32:35]
	s_setprio 3
	s_barrier
	v_mfma_f32_16x16x32_bf16 v[20:23], v[144:147], v[184:187], v[20:23]
	v_mfma_f32_16x16x32_bf16 v[16:19], v[160:163], v[184:187], v[16:19]
	v_mfma_f32_16x16x32_bf16 v[4:7], v[144:147], v[214:217], v[4:7]
	v_mfma_f32_16x16x32_bf16 v[0:3], v[160:163], v[214:217], v[0:3]
	s_setprio 0
	s_add_i32 s58, s58, 2
	s_add_u32 s62, s62, 0x100
	s_addc_u32 s63, s63, 0
	s_cmp_gt_u32 s58, 13
	s_cbranch_scc0 .LBB0_514
	s_and_b64 vcc, exec, s[14:15]
	s_cbranch_vccz .LBB0_517
	s_barrier

; #define PG8_STAGE(bufoff, gbase, voff) do { _Pragma("unroll") for (int _i = 0; _i < 2; ++_i) \
;         __builtin_amdgcn_global_load_lds((const unsigned*)((const char*)(gbase) + (voff)[_i]), (PG8_LAS unsigned*)(lds + (bufoff) + ldsw + _i * 8192), 16, 0, 0); } while (0)
; #define PG8_LDA(dst, b, h) do { _Pragma("unroll") for (int m = 0; m < 4; ++m) _Pragma("unroll") for (int k = 0; k < 2; ++k) dst[m][k] = *(const PG8_LAS bf16x8*)(lds + PG8_SA(b, h) + aoff + m * 2048 + k * 1024); } while (0)
; #define PG8_MMA(ai, bj, At, Bt) do { __builtin_amdgcn_s_setprio(1); _Pragma("unroll") for (int m = 0; m < 4; ++m) _Pragma("unroll") for (int n = 0; n < 2; ++n) _Pragma("unroll") for (int k = 0; k < 2; ++k) \
;         acc[ai][bj][m][n] = __builtin_amdgcn_mfma_f32_16x16x32_bf16(Bt[n][k], At[m][k], acc[ai][bj][m][n], 0, 0, 0); __builtin_amdgcn_s_setprio(0); } while (0)
; #define PG8_WAIT_L(n) asm volatile("s_waitcnt lgkmcnt(" #n ")" ::: "memory")
; #define PG8_WAIT_V8_UNLESS(flag) asm volatile("s_cmp_lg_i32 %0, 0\n\ts_cbranch_scc1 .Lpg8rx%=\n\ts_waitcnt vmcnt(8)\n.Lpg8rx%=:" :: "s"(__builtin_amdgcn_readfirstlane(flag)) : "scc", "memory")
; #define PG8_BAR __builtin_amdgcn_s_barrier()
; #define PG8_SCHED __builtin_amdgcn_sched_barrier(0)
; template <class Epi, class Sched, bool ALIGN_EPI = false, bool SP2 = false>
; __device__ __forceinline__ void gemm_phase(PG8_LAS unsigned char* lds, const Gemm g, const Sched& S, const Epi& E) {
;     ...
;             PG8_WAIT_V8_UNLESS(rx); PG8_WAIT_L(0); PG8_BAR; PG8_MMA(0, 0, At, B0); PG8_MMA(0, 1, At, B1); PG8_BAR; PG8_SCHED;
;             PG8_STAGE(PG8_SB(0, 0), b2, voffB); PG8_STAGE(PG8_SB(0, 1), b2 + hstep, voffB); PG8_STAGE(PG8_SA(0, 0), a2, voffA); PG8_SCHED; PG8_LDA(At, 0, 1);
;             PG8_WAIT_V8_UNLESS(rx); PG8_WAIT_L(0); PG8_BAR; PG8_MMA(1, 0, At, B0); PG8_MMA(1, 1, At, B1); PG8_BAR; PG8_SCHED;
.Lpg8rx4:
	s_waitcnt lgkmcnt(0)
	s_setprio 2
	s_barrier
	v_mfma_f32_16x16x32_bf16 v[124:127], v[132:135], v[176:179], v[124:127]
	v_mfma_f32_16x16x32_bf16 v[120:123], v[140:143], v[176:179], v[120:123]
	v_mfma_f32_16x16x32_bf16 v[108:111], v[132:135], v[204:207], v[108:111]
	v_mfma_f32_16x16x32_bf16 v[104:107], v[140:143], v[204:207], v[104:107]
	v_mfma_f32_16x16x32_bf16 v[92:95], v[132:135], v[212:215], v[92:95]
	v_mfma_f32_16x16x32_bf16 v[88:91], v[140:143], v[212:215], v[88:91]
	v_mfma_f32_16x16x32_bf16 v[76:79], v[132:135], v[220:223], v[76:79]
	v_mfma_f32_16x16x32_bf16 v[72:75], v[140:143], v[220:223], v[72:75]
	v_mfma_f32_16x16x32_bf16 v[124:127], v[136:139], v[186:189], v[124:127]
	v_mfma_f32_16x16x32_bf16 v[120:123], v[144:147], v[186:189], v[120:123]
	v_mfma_f32_16x16x32_bf16 v[108:111], v[136:139], v[208:211], v[108:111]
	v_mfma_f32_16x16x32_bf16 v[104:107], v[144:147], v[208:211], v[104:107]
	v_mfma_f32_16x16x32_bf16 v[92:95], v[136:139], v[216:219], v[92:95]
	v_mfma_f32_16x16x32_bf16 v[88:91], v[144:147], v[216:219], v[88:91]
	v_mfma_f32_16x16x32_bf16 v[76:79], v[136:139], v[224:227], v[76:79]
	v_mfma_f32_16x16x32_bf16 v[72:75], v[144:147], v[224:227], v[72:75]
	v_mfma_f32_16x16x32_bf16 v[116:119], v[148:151], v[176:179], v[116:119]
	v_mfma_f32_16x16x32_bf16 v[112:115], v[168:171], v[176:179], v[112:115]
	v_mfma_f32_16x16x32_bf16 v[100:103], v[148:151], v[204:207], v[100:103]
	v_mfma_f32_16x16x32_bf16 v[96:99], v[168:171], v[204:207], v[96:99]
	v_mfma_f32_16x16x32_bf16 v[84:87], v[148:151], v[212:215], v[84:87]
	v_mfma_f32_16x16x32_bf16 v[80:83], v[168:171], v[212:215], v[80:83]
	v_mfma_f32_16x16x32_bf16 v[68:71], v[148:151], v[220:223], v[68:71]
	v_mfma_f32_16x16x32_bf16 v[64:67], v[168:171], v[220:223], v[64:67]
	v_mfma_f32_16x16x32_bf16 v[116:119], v[164:167], v[186:189], v[116:119]
	v_mfma_f32_16x16x32_bf16 v[112:115], v[172:175], v[186:189], v[112:115]
	v_mfma_f32_16x16x32_bf16 v[100:103], v[164:167], v[208:211], v[100:103]
	v_mfma_f32_16x16x32_bf16 v[96:99], v[172:175], v[208:211], v[96:99]
	s_setprio 3
	s_barrier
	v_mfma_f32_16x16x32_bf16 v[84:87], v[164:167], v[216:219], v[84:87]
	v_mfma_f32_16x16x32_bf16 v[80:83], v[172:175], v[216:219], v[80:83]
	v_mfma_f32_16x16x32_bf16 v[68:71], v[164:167], v[224:227], v[68:71]
	v_mfma_f32_16x16x32_bf16 v[64:67], v[172:175], v[224:227], v[64:67]
	s_setprio 0
	ds_read_b128 v[176:179], v185 offset:16384
	ds_read_b128 v[186:189], v185 offset:17408
	ds_read_b128 v[204:207], v185 offset:18432
	ds_read_b128 v[208:211], v185 offset:19456
	ds_read_b128 v[212:215], v185 offset:20480
	ds_read_b128 v[216:219], v185 offset:21504
	ds_read_b128 v[220:223], v185 offset:22528
	ds_read_b128 v[224:227], v185 offset:23552
	s_add_u32 s60, s28, 0x40000
	s_addc_u32 s61, s29, 0
	s_add_i32 m0, s59, s38
	s_nop 0
	global_load_lds_dwordx4 v154, s[28:29]
	s_add_i32 m0, m0, 0x2000
	s_nop 0
	global_load_lds_dwordx4 v158, s[28:29]
	s_add_i32 m0, s62, s38
	s_nop 0
	global_load_lds_dwordx4 v154, s[60:61]
	s_add_i32 m0, m0, 0x2000
	s_nop 0
	global_load_lds_dwordx4 v158, s[60:61]
	s_mov_b32 m0, s21
	s_nop 0
	global_load_lds_dwordx4 v152, s[30:31]
	s_mov_b32 m0, s23
	s_nop 0
	global_load_lds_dwordx4 v156, s[30:31]
	s_cmp_lg_i32 s63, 0
	s_cbranch_scc1 .Lpg8rx5
	s_waitcnt vmcnt(8)
.Lpg8rx5:
	s_waitcnt lgkmcnt(0)
	s_setprio 2
	s_barrier
	v_mfma_f32_16x16x32_bf16 v[60:63], v[132:135], v[176:179], v[60:63]
	v_mfma_f32_16x16x32_bf16 v[56:59], v[140:143], v[176:179], v[56:59]
	v_mfma_f32_16x16x32_bf16 v[44:47], v[132:135], v[204:207], v[44:47]
	v_mfma_f32_16x16x32_bf16 v[40:43], v[140:143], v[204:207], v[40:43]
	v_mfma_f32_16x16x32_bf16 v[28:31], v[132:135], v[212:215], v[28:31]
	v_mfma_f32_16x16x32_bf16 v[24:27], v[140:143], v[212:215], v[24:27]
	v_mfma_f32_16x16x32_bf16 v[12:15], v[132:135], v[220:223], v[12:15]
	v_mfma_f32_16x16x32_bf16 v[8:11], v[140:143], v[220:223], v[8:11]
	v_mfma_f32_16x16x32_bf16 v[60:63], v[136:139], v[186:189], v[60:63]
	v_mfma_f32_16x16x32_bf16 v[56:59], v[144:147], v[186:189], v[56:59]
	v_mfma_f32_16x16x32_bf16 v[44:47], v[136:139], v[208:211], v[44:47]
	v_mfma_f32_16x16x32_bf16 v[40:43], v[144:147], v[208:211], v[40:43]
	v_mfma_f32_16x16x32_bf16 v[28:31], v[136:139], v[216:219], v[28:31]
	v_mfma_f32_16x16x32_bf16 v[24:27], v[144:147], v[216:219], v[24:27]
	v_mfma_f32_16x16x32_bf16 v[12:15], v[136:139], v[224:227], v[12:15]
	v_mfma_f32_16x16x32_bf16 v[8:11], v[144:147], v[224:227], v[8:11]
	v_mfma_f32_16x16x32_bf16 v[52:55], v[148:151], v[176:179], v[52:55]
	v_mfma_f32_16x16x32_bf16 v[48:51], v[168:171], v[176:179], v[48:51]
	v_mfma_f32_16x16x32_bf16 v[36:39], v[148:151], v[204:207], v[36:39]
	v_mfma_f32_16x16x32_bf16 v[32:35], v[168:171], v[204:207], v[32:35]
	v_mfma_f32_16x16x32_bf16 v[20:23], v[148:151], v[212:215], v[20:23]
	v_mfma_f32_16x16x32_bf16 v[16:19], v[168:171], v[212:215], v[16:19]
	v_mfma_f32_16x16x32_bf16 v[4:7], v[148:151], v[220:223], v[4:7]
	v_mfma_f32_16x16x32_bf16 v[0:3], v[168:171], v[220:223], v[0:3]
	v_mfma_f32_16x16x32_bf16 v[52:55], v[164:167], v[186:189], v[52:55]
	v_mfma_f32_16x16x32_bf16 v[48:51], v[172:175], v[186:189], v[48:51]
	v_mfma_f32_16x16x32_bf16 v[36:39], v[164:167], v[208:211], v[36:39]
	v_mfma_f32_16x16x32_bf16 v[32:35], v[172:175], v[208:211], v[32:35]
	s_setprio 3
	s_barrier
; #define PG8_STAGE(bufoff, gbase, voff) do { _Pragma("unroll") for (int _i = 0; _i < 2; ++_i) \
;         __builtin_amdgcn_global_load_lds((const unsigned*)((const char*)(gbase) + (voff)[_i]), (PG8_LAS unsigned*)(lds + (bufoff) + ldsw + _i * 8192), 16, 0, 0); } while (0)
; #define PG8_LDA(dst, b, h) do { _Pragma("unroll") for (int m = 0; m < 4; ++m) _Pragma("unroll") for (int k = 0; k < 2; ++k) dst[m][k] = *(const PG8_LAS bf16x8*)(lds + PG8_SA(b, h) + aoff + m * 2048 + k * 1024); } while (0)
; #define PG8_LDB(dst, b, h) do { _Pragma("unroll") for (int n = 0; n < 2; ++n) _Pragma("unroll") for (int k = 0; k < 2; ++k) dst[n][k] = *(const PG8_LAS bf16x8*)(lds + PG8_SB(b, h) + boff + n * 2048 + k * 1024); } while (0)
; #define PG8_MMA(ai, bj, At, Bt) do { __builtin_amdgcn_s_setprio(1); _Pragma("unroll") for (int m = 0; m < 4; ++m) _Pragma("unroll") for (int n = 0; n < 2; ++n) _Pragma("unroll") for (int k = 0; k < 2; ++k) \
;         acc[ai][bj][m][n] = __builtin_amdgcn_mfma_f32_16x16x32_bf16(Bt[n][k], At[m][k], acc[ai][bj][m][n], 0, 0, 0); __builtin_amdgcn_s_setprio(0); } while (0)
; template <class Epi, class Sched, bool ALIGN_EPI = false, bool SP2 = false>
; __device__ __forceinline__ void gemm_phase(PG8_LAS unsigned char* lds, const Gemm g, const Sched& S, const Epi& E) {
;     ...
;             PG8_STAGE(PG8_SA(1, 1), a1 + hstep, voffA); PG8_SCHED; PG8_LDB(B0, 0, 0); PG8_LDB(B1, 0, 1); PG8_SCHED; PG8_LDA(At, 0, 0);
;             PG8_WAIT_V8_UNLESS(rx); PG8_WAIT_L(0); PG8_BAR; PG8_MMA(0, 0, At, B0); PG8_MMA(0, 1, At, B1); PG8_BAR; PG8_SCHED;
;             PG8_STAGE(PG8_SB(0, 0), b2, voffB); PG8_STAGE(PG8_SB(0, 1), b2 + hstep, voffB); PG8_STAGE(PG8_SA(0, 0), a2, voffA); PG8_SCHED; PG8_LDA(At, 0, 1);
;             PG8_WAIT_V8_UNLESS(rx); PG8_WAIT_L(0); PG8_BAR; PG8_MMA(1, 0, At, B0); PG8_MMA(1, 1, At, B1); PG8_BAR; PG8_SCHED;
;             PG8_STAGE(PG8_SA(0, 1), a2 + hstep, voffA); PG8_SCHED; PG8_LDB(B0, 1, 0); PG8_LDB(B1, 1, 1); PG8_SCHED; PG8_LDA(At, 1, 0);
;             PG8_WAIT_V(8); PG8_WAIT_L(0); PG8_BAR; PG8_MMA(0, 0, At, B0); PG8_MMA(0, 1, At, B1); PG8_BAR; PG8_SCHED;
;             PG8_STAGE(PG8_SB(1, 0), b3, voffB); PG8_STAGE(PG8_SB(1, 1), b3 + hstep, voffB); PG8_STAGE(PG8_SA(1, 0), a3, voffA); PG8_SCHED; PG8_LDA(At, 1, 1);
;             PG8_WAIT_V(8); PG8_WAIT_L(0); PG8_BAR; PG8_MMA(1, 0, At, B0); PG8_MMA(1, 1, At, B1); PG8_BAR; PG8_SCHED;
	v_mfma_f32_16x16x32_bf16 v[20:23], v[164:167], v[216:219], v[20:23]
	v_mfma_f32_16x16x32_bf16 v[16:19], v[172:175], v[216:219], v[16:19]
	v_mfma_f32_16x16x32_bf16 v[4:7], v[164:167], v[224:227], v[4:7]
	v_mfma_f32_16x16x32_bf16 v[0:3], v[172:175], v[224:227], v[0:3]
	s_setprio 0
	s_mov_b64 s[98:99], s[30:31]
	s_add_u32 s100, s30, 0x40000
	s_addc_u32 s101, s31, 0
	s_add_i32 s30, 0, 0x18000
	s_add_i32 s31, 0, 0x1c000
	v_add_u32_e32 v144, s30, v183
	v_add_u32_e32 v172, s31, v183
	ds_read_b128 v[132:135], v144
	ds_read_b128 v[136:139], v144 offset:1024
	ds_read_b128 v[140:143], v144 offset:2048
	ds_read_b128 v[144:147], v144 offset:3072
	ds_read_b128 v[148:151], v172
	ds_read_b128 v[164:167], v172 offset:1024
	ds_read_b128 v[168:171], v172 offset:2048
	ds_read_b128 v[172:175], v172 offset:3072
	ds_read_b128 v[176:179], v185 offset:32768
	ds_read_b128 v[186:189], v185 offset:33792
	ds_read_b128 v[204:207], v185 offset:34816
	ds_read_b128 v[208:211], v185 offset:35840
	ds_read_b128 v[212:215], v185 offset:36864
	ds_read_b128 v[216:219], v185 offset:37888
	ds_read_b128 v[220:223], v185 offset:38912
	ds_read_b128 v[224:227], v185 offset:39936
	s_mov_b32 m0, s46
	s_nop 0
	global_load_lds_dwordx4 v152, s[100:101]
	s_mov_b32 m0, s48
	s_nop 0
	global_load_lds_dwordx4 v156, s[100:101]
	s_waitcnt vmcnt(8)
	s_waitcnt lgkmcnt(0)
	s_setprio 2
	s_barrier
	v_mfma_f32_16x16x32_bf16 v[124:127], v[132:135], v[176:179], v[124:127]
	v_mfma_f32_16x16x32_bf16 v[120:123], v[140:143], v[176:179], v[120:123]
	v_mfma_f32_16x16x32_bf16 v[108:111], v[132:135], v[204:207], v[108:111]
	v_mfma_f32_16x16x32_bf16 v[104:107], v[140:143], v[204:207], v[104:107]
	v_mfma_f32_16x16x32_bf16 v[92:95], v[132:135], v[212:215], v[92:95]
	v_mfma_f32_16x16x32_bf16 v[88:91], v[140:143], v[212:215], v[88:91]
	v_mfma_f32_16x16x32_bf16 v[76:79], v[132:135], v[220:223], v[76:79]
	v_mfma_f32_16x16x32_bf16 v[72:75], v[140:143], v[220:223], v[72:75]
	v_mfma_f32_16x16x32_bf16 v[124:127], v[136:139], v[186:189], v[124:127]
	v_mfma_f32_16x16x32_bf16 v[120:123], v[144:147], v[186:189], v[120:123]
	v_mfma_f32_16x16x32_bf16 v[108:111], v[136:139], v[208:211], v[108:111]
	v_mfma_f32_16x16x32_bf16 v[104:107], v[144:147], v[208:211], v[104:107]
	v_mfma_f32_16x16x32_bf16 v[92:95], v[136:139], v[216:219], v[92:95]
	v_mfma_f32_16x16x32_bf16 v[88:91], v[144:147], v[216:219], v[88:91]
	v_mfma_f32_16x16x32_bf16 v[76:79], v[136:139], v[224:227], v[76:79]
	v_mfma_f32_16x16x32_bf16 v[72:75], v[144:147], v[224:227], v[72:75]
	v_mfma_f32_16x16x32_bf16 v[116:119], v[148:151], v[176:179], v[116:119]
	v_mfma_f32_16x16x32_bf16 v[112:115], v[168:171], v[176:179], v[112:115]
	v_mfma_f32_16x16x32_bf16 v[100:103], v[148:151], v[204:207], v[100:103]
	v_mfma_f32_16x16x32_bf16 v[96:99], v[168:171], v[204:207], v[96:99]
	v_mfma_f32_16x16x32_bf16 v[84:87], v[148:151], v[212:215], v[84:87]
	v_mfma_f32_16x16x32_bf16 v[80:83], v[168:171], v[212:215], v[80:83]
	v_mfma_f32_16x16x32_bf16 v[68:71], v[148:151], v[220:223], v[68:71]
	v_mfma_f32_16x16x32_bf16 v[64:67], v[168:171], v[220:223], v[64:67]
	v_mfma_f32_16x16x32_bf16 v[116:119], v[164:167], v[186:189], v[116:119]
	v_mfma_f32_16x16x32_bf16 v[112:115], v[172:175], v[186:189], v[112:115]
	v_mfma_f32_16x16x32_bf16 v[100:103], v[164:167], v[208:211], v[100:103]
	v_mfma_f32_16x16x32_bf16 v[96:99], v[172:175], v[208:211], v[96:99]
	s_setprio 3
	s_barrier
; #define PG8_STAGE(bufoff, gbase, voff) do { _Pragma("unroll") for (int _i = 0; _i < 2; ++_i) \
;         __builtin_amdgcn_global_load_lds((const unsigned*)((const char*)(gbase) + (voff)[_i]), (PG8_LAS unsigned*)(lds + (bufoff) + ldsw + _i * 8192), 16, 0, 0); } while (0)
; #define PG8_LDA(dst, b, h) do { _Pragma("unroll") for (int m = 0; m < 4; ++m) _Pragma("unroll") for (int k = 0; k < 2; ++k) dst[m][k] = *(const PG8_LAS bf16x8*)(lds + PG8_SA(b, h) + aoff + m * 2048 + k * 1024); } while (0)
; #define PG8_LDB(dst, b, h) do { _Pragma("unroll") for (int n = 0; n < 2; ++n) _Pragma("unroll") for (int k = 0; k < 2; ++k) dst[n][k] = *(const PG8_LAS bf16x8*)(lds + PG8_SB(b, h) + boff + n * 2048 + k * 1024); } while (0)
; #define PG8_MMA(ai, bj, At, Bt) do { __builtin_amdgcn_s_setprio(1); _Pragma("unroll") for (int m = 0; m < 4; ++m) _Pragma("unroll") for (int n = 0; n < 2; ++n) _Pragma("unroll") for (int k = 0; k < 2; ++k) \
;         acc[ai][bj][m][n] = __builtin_amdgcn_mfma_f32_16x16x32_bf16(Bt[n][k], At[m][k], acc[ai][bj][m][n], 0, 0, 0); __builtin_amdgcn_s_setprio(0); } while (0)
; #define PG8_WAIT_V(n) asm volatile("s_waitcnt vmcnt(" #n ")" ::: "memory")
; #define PG8_WAIT_L(n) asm volatile("s_waitcnt lgkmcnt(" #n ")" ::: "memory")
; #define PG8_BAR __builtin_amdgcn_s_barrier()
; #define PG8_SCHED __builtin_amdgcn_sched_barrier(0)
; template <class Epi, class Sched, bool ALIGN_EPI = false, bool SP2 = false>
; __device__ __forceinline__ void gemm_phase(PG8_LAS unsigned char* lds, const Gemm g, const Sched& S, const Epi& E) {
;     ...
;         for (int t = 0; t < nt; t += 2) {
;     ...
;             PG8_STAGE(PG8_SA(0, 1), a2 + hstep, voffA); PG8_SCHED; PG8_LDB(B0, 1, 0); PG8_LDB(B1, 1, 1); PG8_SCHED; PG8_LDA(At, 1, 0);
;             PG8_WAIT_V(8); PG8_WAIT_L(0); PG8_BAR; PG8_MMA(0, 0, At, B0); PG8_MMA(0, 1, At, B1); PG8_BAR; PG8_SCHED;
;             PG8_STAGE(PG8_SB(1, 0), b3, voffB); PG8_STAGE(PG8_SB(1, 1), b3 + hstep, voffB); PG8_STAGE(PG8_SA(1, 0), a3, voffA); PG8_SCHED; PG8_LDA(At, 1, 1);
;             PG8_WAIT_V(8); PG8_WAIT_L(0); PG8_BAR; PG8_MMA(1, 0, At, B0); PG8_MMA(1, 1, At, B1); PG8_BAR; PG8_SCHED;
	v_mfma_f32_16x16x32_bf16 v[84:87], v[164:167], v[216:219], v[84:87]
	v_mfma_f32_16x16x32_bf16 v[80:83], v[172:175], v[216:219], v[80:83]
	v_mfma_f32_16x16x32_bf16 v[68:71], v[164:167], v[224:227], v[68:71]
	v_mfma_f32_16x16x32_bf16 v[64:67], v[172:175], v[224:227], v[64:67]
	s_setprio 0
	ds_read_b128 v[176:179], v185 offset:49152
	ds_read_b128 v[186:189], v185 offset:50176
	ds_read_b128 v[204:207], v185 offset:51200
	ds_read_b128 v[208:211], v185 offset:52224
	ds_read_b128 v[212:215], v185 offset:53248
	ds_read_b128 v[216:219], v185 offset:54272
	ds_read_b128 v[220:223], v185 offset:55296
	ds_read_b128 v[224:227], v185 offset:56320
	s_add_u32 s100, s28, 0x80
	s_addc_u32 s101, s29, 0
	s_add_u32 s28, s28, 0x40080
	s_addc_u32 s29, s29, 0
	s_add_u32 s98, s98, 0x80
	s_addc_u32 s99, s99, 0
	s_add_i32 m0, s30, s38
	s_nop 0
	global_load_lds_dwordx4 v154, s[100:101]
	s_add_i32 m0, m0, 0x2000
	s_nop 0
	global_load_lds_dwordx4 v158, s[100:101]
	s_add_i32 m0, s31, s38
	s_nop 0
	global_load_lds_dwordx4 v154, s[28:29]
	s_add_i32 m0, m0, 0x2000
	s_nop 0
	global_load_lds_dwordx4 v158, s[28:29]
	s_mov_b32 m0, s50
	s_nop 0
	global_load_lds_dwordx4 v152, s[98:99]
	s_mov_b32 m0, s51
	s_nop 0
	global_load_lds_dwordx4 v156, s[98:99]
	s_waitcnt vmcnt(8)
	s_waitcnt lgkmcnt(0)
	s_setprio 2
	s_barrier
	v_mfma_f32_16x16x32_bf16 v[60:63], v[132:135], v[176:179], v[60:63]
	v_mfma_f32_16x16x32_bf16 v[56:59], v[140:143], v[176:179], v[56:59]
	v_mfma_f32_16x16x32_bf16 v[44:47], v[132:135], v[204:207], v[44:47]
	v_mfma_f32_16x16x32_bf16 v[40:43], v[140:143], v[204:207], v[40:43]
	v_mfma_f32_16x16x32_bf16 v[28:31], v[132:135], v[212:215], v[28:31]
	v_mfma_f32_16x16x32_bf16 v[24:27], v[140:143], v[212:215], v[24:27]
	v_mfma_f32_16x16x32_bf16 v[12:15], v[132:135], v[220:223], v[12:15]
	v_mfma_f32_16x16x32_bf16 v[8:11], v[140:143], v[220:223], v[8:11]
	v_mfma_f32_16x16x32_bf16 v[60:63], v[136:139], v[186:189], v[60:63]
	v_mfma_f32_16x16x32_bf16 v[56:59], v[144:147], v[186:189], v[56:59]
	v_mfma_f32_16x16x32_bf16 v[44:47], v[136:139], v[208:211], v[44:47]
	v_mfma_f32_16x16x32_bf16 v[40:43], v[144:147], v[208:211], v[40:43]
	v_mfma_f32_16x16x32_bf16 v[28:31], v[136:139], v[216:219], v[28:31]
	v_mfma_f32_16x16x32_bf16 v[24:27], v[144:147], v[216:219], v[24:27]
	v_mfma_f32_16x16x32_bf16 v[12:15], v[136:139], v[224:227], v[12:15]
	v_mfma_f32_16x16x32_bf16 v[8:11], v[144:147], v[224:227], v[8:11]
	v_mfma_f32_16x16x32_bf16 v[52:55], v[148:151], v[176:179], v[52:55]
	v_mfma_f32_16x16x32_bf16 v[48:51], v[168:171], v[176:179], v[48:51]
	v_mfma_f32_16x16x32_bf16 v[36:39], v[148:151], v[204:207], v[36:39]
	v_mfma_f32_16x16x32_bf16 v[32:35], v[168:171], v[204:207], v[32:35]
	v_mfma_f32_16x16x32_bf16 v[20:23], v[148:151], v[212:215], v[20:23]
	v_mfma_f32_16x16x32_bf16 v[16:19], v[168:171], v[212:215], v[16:19]
	v_mfma_f32_16x16x32_bf16 v[4:7], v[148:151], v[220:223], v[4:7]
	v_mfma_f32_16x16x32_bf16 v[0:3], v[168:171], v[220:223], v[0:3]
	v_mfma_f32_16x16x32_bf16 v[52:55], v[164:167], v[186:189], v[52:55]
	v_mfma_f32_16x16x32_bf16 v[48:51], v[172:175], v[186:189], v[48:51]
	v_mfma_f32_16x16x32_bf16 v[36:39], v[164:167], v[208:211], v[36:39]
	v_mfma_f32_16x16x32_bf16 v[32:35], v[172:175], v[208:211], v[32:35]
	s_setprio 3
	s_barrier
	v_mfma_f32_16x16x32_bf16 v[20:23], v[164:167], v[216:219], v[20:23]
	v_mfma_f32_16x16x32_bf16 v[16:19], v[172:175], v[216:219], v[16:19]
	v_mfma_f32_16x16x32_bf16 v[4:7], v[164:167], v[224:227], v[4:7]
	v_mfma_f32_16x16x32_bf16 v[0:3], v[172:175], v[224:227], v[0:3]
	s_setprio 0
	s_add_i32 s58, s58, 2
	s_add_u32 s40, s40, 0x100
	s_addc_u32 s41, s41, 0
	s_cmp_gt_u32 s58, 13
	s_cbranch_scc0 .LBB0_611
	s_and_b64 vcc, exec, s[8:9]
	s_cbranch_vccz .LBB0_614
	s_barrier

; #define PG8_STAGE(bufoff, gbase, voff) do { _Pragma("unroll") for (int _i = 0; _i < 2; ++_i) \
;         __builtin_amdgcn_global_load_lds((const unsigned*)((const char*)(gbase) + (voff)[_i]), (PG8_LAS unsigned*)(lds + (bufoff) + ldsw + _i * 8192), 16, 0, 0); } while (0)
; #define PG8_LDA(dst, b, h) do { _Pragma("unroll") for (int m = 0; m < 4; ++m) _Pragma("unroll") for (int k = 0; k < 2; ++k) dst[m][k] = *(const PG8_LAS bf16x8*)(lds + PG8_SA(b, h) + aoff + m * 2048 + k * 1024); } while (0)
; #define PG8_LDB(dst, b, h) do { _Pragma("unroll") for (int n = 0; n < 2; ++n) _Pragma("unroll") for (int k = 0; k < 2; ++k) dst[n][k] = *(const PG8_LAS bf16x8*)(lds + PG8_SB(b, h) + boff + n * 2048 + k * 1024); } while (0)
; #define PG8_MMA(ai, bj, At, Bt) do { __builtin_amdgcn_s_setprio(1); _Pragma("unroll") for (int m = 0; m < 4; ++m) _Pragma("unroll") for (int n = 0; n < 2; ++n) _Pragma("unroll") for (int k = 0; k < 2; ++k) \
;         acc[ai][bj][m][n] = __builtin_amdgcn_mfma_f32_16x16x32_bf16(Bt[n][k], At[m][k], acc[ai][bj][m][n], 0, 0, 0); __builtin_amdgcn_s_setprio(0); } while (0)
; #define PG8_WAIT_L(n) asm volatile("s_waitcnt lgkmcnt(" #n ")" ::: "memory")
; #define PG8_WAIT_V8_UNLESS(flag) asm volatile("s_cmp_lg_i32 %0, 0\n\ts_cbranch_scc1 .Lpg8rx%=\n\ts_waitcnt vmcnt(8)\n.Lpg8rx%=:" :: "s"(__builtin_amdgcn_readfirstlane(flag)) : "scc", "memory")
; #define PG8_BAR __builtin_amdgcn_s_barrier()
; #define PG8_SCHED __builtin_amdgcn_sched_barrier(0)
; template <class Epi, class Sched, bool ALIGN_EPI = false, bool SP2 = false>
; __device__ __forceinline__ void gemm_phase(PG8_LAS unsigned char* lds, const Gemm g, const Sched& S, const Epi& E) {
;     ...
;             PG8_STAGE(PG8_SA(1, 1), a1 + hstep, voffA); PG8_SCHED; PG8_LDB(B0, 0, 0); PG8_LDB(B1, 0, 1); PG8_SCHED; PG8_LDA(At, 0, 0);
;             PG8_WAIT_V8_UNLESS(rx); PG8_WAIT_L(0); PG8_BAR; PG8_MMA(0, 0, At, B0); PG8_MMA(0, 1, At, B1); PG8_BAR; PG8_SCHED;
;             PG8_STAGE(PG8_SB(0, 0), b2, voffB); PG8_STAGE(PG8_SB(0, 1), b2 + hstep, voffB); PG8_STAGE(PG8_SA(0, 0), a2, voffA); PG8_SCHED; PG8_LDA(At, 0, 1);
;             PG8_WAIT_V8_UNLESS(rx); PG8_WAIT_L(0); PG8_BAR; PG8_MMA(1, 0, At, B0); PG8_MMA(1, 1, At, B1); PG8_BAR; PG8_SCHED;
.Lpg8rx6:
	s_waitcnt lgkmcnt(0)
	s_setprio 2
	s_barrier
	v_mfma_f32_16x16x32_bf16 v[152:155], v[120:123], v[164:167], v[152:155]
	v_mfma_f32_16x16x32_bf16 v[148:151], v[132:135], v[164:167], v[148:151]
	v_mfma_f32_16x16x32_bf16 v[108:111], v[120:123], v[172:175], v[108:111]
	v_mfma_f32_16x16x32_bf16 v[104:107], v[132:135], v[172:175], v[104:107]
	v_mfma_f32_16x16x32_bf16 v[92:95], v[120:123], v[180:183], v[92:95]
	v_mfma_f32_16x16x32_bf16 v[88:91], v[132:135], v[180:183], v[88:91]
	v_mfma_f32_16x16x32_bf16 v[76:79], v[120:123], v[188:191], v[76:79]
	v_mfma_f32_16x16x32_bf16 v[72:75], v[132:135], v[188:191], v[72:75]
	v_mfma_f32_16x16x32_bf16 v[152:155], v[128:131], v[168:171], v[152:155]
	v_mfma_f32_16x16x32_bf16 v[148:151], v[136:139], v[168:171], v[148:151]
	v_mfma_f32_16x16x32_bf16 v[108:111], v[128:131], v[176:179], v[108:111]
	v_mfma_f32_16x16x32_bf16 v[104:107], v[136:139], v[176:179], v[104:107]
	v_mfma_f32_16x16x32_bf16 v[92:95], v[128:131], v[184:187], v[92:95]
	v_mfma_f32_16x16x32_bf16 v[88:91], v[136:139], v[184:187], v[88:91]
	v_mfma_f32_16x16x32_bf16 v[76:79], v[128:131], v[214:217], v[76:79]
	v_mfma_f32_16x16x32_bf16 v[72:75], v[136:139], v[214:217], v[72:75]
	v_mfma_f32_16x16x32_bf16 v[124:127], v[140:143], v[164:167], v[124:127]
	v_mfma_f32_16x16x32_bf16 v[112:115], v[156:159], v[164:167], v[112:115]
	v_mfma_f32_16x16x32_bf16 v[100:103], v[140:143], v[172:175], v[100:103]
	v_mfma_f32_16x16x32_bf16 v[96:99], v[156:159], v[172:175], v[96:99]
	v_mfma_f32_16x16x32_bf16 v[84:87], v[140:143], v[180:183], v[84:87]
	v_mfma_f32_16x16x32_bf16 v[80:83], v[156:159], v[180:183], v[80:83]
	v_mfma_f32_16x16x32_bf16 v[68:71], v[140:143], v[188:191], v[68:71]
	v_mfma_f32_16x16x32_bf16 v[64:67], v[156:159], v[188:191], v[64:67]
	v_mfma_f32_16x16x32_bf16 v[124:127], v[144:147], v[168:171], v[124:127]
	v_mfma_f32_16x16x32_bf16 v[112:115], v[160:163], v[168:171], v[112:115]
	v_mfma_f32_16x16x32_bf16 v[100:103], v[144:147], v[176:179], v[100:103]
	v_mfma_f32_16x16x32_bf16 v[96:99], v[160:163], v[176:179], v[96:99]
	s_setprio 3
	s_barrier
	v_mfma_f32_16x16x32_bf16 v[84:87], v[144:147], v[184:187], v[84:87]
	v_mfma_f32_16x16x32_bf16 v[80:83], v[160:163], v[184:187], v[80:83]
	v_mfma_f32_16x16x32_bf16 v[68:71], v[144:147], v[214:217], v[68:71]
	v_mfma_f32_16x16x32_bf16 v[64:67], v[160:163], v[214:217], v[64:67]
	s_setprio 0
	ds_read_b128 v[164:167], v248 offset:16384
	ds_read_b128 v[168:171], v248 offset:17408
	ds_read_b128 v[172:175], v248 offset:18432
	ds_read_b128 v[176:179], v248 offset:19456
	ds_read_b128 v[180:183], v248 offset:20480
	ds_read_b128 v[184:187], v248 offset:21504
	ds_read_b128 v[188:191], v248 offset:22528
	ds_read_b128 v[214:217], v248 offset:23552
	s_add_u32 s58, s28, 0x100000
	s_addc_u32 s59, s29, 0
	s_add_i32 m0, s57, s39
	s_nop 0
	global_load_lds_dwordx4 v194, s[28:29]
	s_add_i32 m0, m0, 0x2000
	s_nop 0
	global_load_lds_dwordx4 v208, s[28:29]
	s_add_i32 m0, s60, s39
	s_nop 0
	global_load_lds_dwordx4 v194, s[58:59]
	s_add_i32 m0, m0, 0x2000
	s_nop 0
	global_load_lds_dwordx4 v208, s[58:59]
	s_mov_b32 m0, s25
	s_nop 0
	global_load_lds_dwordx4 v204, s[30:31]
	s_mov_b32 m0, s42
	s_nop 0
	global_load_lds_dwordx4 v206, s[30:31]
	s_cmp_lg_i32 s61, 0
	s_cbranch_scc1 .Lpg8rx7
	s_waitcnt vmcnt(8)
.Lpg8rx7:
	s_waitcnt lgkmcnt(0)
	s_setprio 2
	s_barrier
	v_mfma_f32_16x16x32_bf16 v[60:63], v[120:123], v[164:167], v[60:63]
	v_mfma_f32_16x16x32_bf16 v[56:59], v[132:135], v[164:167], v[56:59]
	v_mfma_f32_16x16x32_bf16 v[44:47], v[120:123], v[172:175], v[44:47]
	v_mfma_f32_16x16x32_bf16 v[40:43], v[132:135], v[172:175], v[40:43]
	v_mfma_f32_16x16x32_bf16 v[28:31], v[120:123], v[180:183], v[28:31]
	v_mfma_f32_16x16x32_bf16 v[24:27], v[132:135], v[180:183], v[24:27]
	v_mfma_f32_16x16x32_bf16 v[12:15], v[120:123], v[188:191], v[12:15]
	v_mfma_f32_16x16x32_bf16 v[8:11], v[132:135], v[188:191], v[8:11]
	v_mfma_f32_16x16x32_bf16 v[60:63], v[128:131], v[168:171], v[60:63]
	v_mfma_f32_16x16x32_bf16 v[56:59], v[136:139], v[168:171], v[56:59]
	v_mfma_f32_16x16x32_bf16 v[44:47], v[128:131], v[176:179], v[44:47]
	v_mfma_f32_16x16x32_bf16 v[40:43], v[136:139], v[176:179], v[40:43]
	v_mfma_f32_16x16x32_bf16 v[28:31], v[128:131], v[184:187], v[28:31]
	v_mfma_f32_16x16x32_bf16 v[24:27], v[136:139], v[184:187], v[24:27]
	v_mfma_f32_16x16x32_bf16 v[12:15], v[128:131], v[214:217], v[12:15]
	v_mfma_f32_16x16x32_bf16 v[8:11], v[136:139], v[214:217], v[8:11]
	v_mfma_f32_16x16x32_bf16 v[52:55], v[140:143], v[164:167], v[52:55]
	v_mfma_f32_16x16x32_bf16 v[48:51], v[156:159], v[164:167], v[48:51]
	v_mfma_f32_16x16x32_bf16 v[36:39], v[140:143], v[172:175], v[36:39]
	v_mfma_f32_16x16x32_bf16 v[32:35], v[156:159], v[172:175], v[32:35]
	v_mfma_f32_16x16x32_bf16 v[20:23], v[140:143], v[180:183], v[20:23]
	v_mfma_f32_16x16x32_bf16 v[16:19], v[156:159], v[180:183], v[16:19]
	v_mfma_f32_16x16x32_bf16 v[4:7], v[140:143], v[188:191], v[4:7]
	v_mfma_f32_16x16x32_bf16 v[0:3], v[156:159], v[188:191], v[0:3]
	v_mfma_f32_16x16x32_bf16 v[52:55], v[144:147], v[168:171], v[52:55]
	v_mfma_f32_16x16x32_bf16 v[48:51], v[160:163], v[168:171], v[48:51]
	v_mfma_f32_16x16x32_bf16 v[36:39], v[144:147], v[176:179], v[36:39]
	v_mfma_f32_16x16x32_bf16 v[32:35], v[160:163], v[176:179], v[32:35]
	s_setprio 3
	s_barrier
; #define PG8_STAGE(bufoff, gbase, voff) do { _Pragma("unroll") for (int _i = 0; _i < 2; ++_i) \
;         __builtin_amdgcn_global_load_lds((const unsigned*)((const char*)(gbase) + (voff)[_i]), (PG8_LAS unsigned*)(lds + (bufoff) + ldsw + _i * 8192), 16, 0, 0); } while (0)
; #define PG8_LDA(dst, b, h) do { _Pragma("unroll") for (int m = 0; m < 4; ++m) _Pragma("unroll") for (int k = 0; k < 2; ++k) dst[m][k] = *(const PG8_LAS bf16x8*)(lds + PG8_SA(b, h) + aoff + m * 2048 + k * 1024); } while (0)
; #define PG8_LDB(dst, b, h) do { _Pragma("unroll") for (int n = 0; n < 2; ++n) _Pragma("unroll") for (int k = 0; k < 2; ++k) dst[n][k] = *(const PG8_LAS bf16x8*)(lds + PG8_SB(b, h) + boff + n * 2048 + k * 1024); } while (0)
; #define PG8_MMA(ai, bj, At, Bt) do { __builtin_amdgcn_s_setprio(1); _Pragma("unroll") for (int m = 0; m < 4; ++m) _Pragma("unroll") for (int n = 0; n < 2; ++n) _Pragma("unroll") for (int k = 0; k < 2; ++k) \
;         acc[ai][bj][m][n] = __builtin_amdgcn_mfma_f32_16x16x32_bf16(Bt[n][k], At[m][k], acc[ai][bj][m][n], 0, 0, 0); __builtin_amdgcn_s_setprio(0); } while (0)
; #define PG8_WAIT_V(n) asm volatile("s_waitcnt vmcnt(" #n ")" ::: "memory")
; #define PG8_WAIT_L(n) asm volatile("s_waitcnt lgkmcnt(" #n ")" ::: "memory")
; #define PG8_BAR __builtin_amdgcn_s_barrier()
; #define PG8_SCHED __builtin_amdgcn_sched_barrier(0)
; template <class Epi, class Sched, bool ALIGN_EPI = false, bool SP2 = false>
; __device__ __forceinline__ void gemm_phase(PG8_LAS unsigned char* lds, const Gemm g, const Sched& S, const Epi& E) {
;     ...
;             PG8_STAGE(PG8_SA(0, 1), a2 + hstep, voffA); PG8_SCHED; PG8_LDB(B0, 1, 0); PG8_LDB(B1, 1, 1); PG8_SCHED; PG8_LDA(At, 1, 0);
;             PG8_WAIT_V(8); PG8_WAIT_L(0); PG8_BAR; PG8_MMA(0, 0, At, B0); PG8_MMA(0, 1, At, B1); PG8_BAR; PG8_SCHED;
	v_mfma_f32_16x16x32_bf16 v[20:23], v[144:147], v[184:187], v[20:23]
	v_mfma_f32_16x16x32_bf16 v[16:19], v[160:163], v[184:187], v[16:19]
	v_mfma_f32_16x16x32_bf16 v[4:7], v[144:147], v[214:217], v[4:7]
	v_mfma_f32_16x16x32_bf16 v[0:3], v[160:163], v[214:217], v[0:3]
	s_setprio 0
	s_mov_b64 s[98:99], s[30:31]
	s_add_u32 s100, s30, 0x100000
	s_addc_u32 s101, s31, 0
	s_add_i32 s30, 0, 0x18000
	s_add_i32 s31, 0, 0x1c000
	v_add_u32_e32 v136, s30, v247
	v_add_u32_e32 v160, s31, v247
	ds_read_b128 v[120:123], v136
	ds_read_b128 v[128:131], v136 offset:1024
	ds_read_b128 v[132:135], v136 offset:2048
	ds_read_b128 v[136:139], v136 offset:3072
	ds_read_b128 v[140:143], v160
	ds_read_b128 v[144:147], v160 offset:1024
	ds_read_b128 v[156:159], v160 offset:2048
	ds_read_b128 v[160:163], v160 offset:3072
	ds_read_b128 v[164:167], v248 offset:32768
	ds_read_b128 v[168:171], v248 offset:33792
	ds_read_b128 v[172:175], v248 offset:34816
	ds_read_b128 v[176:179], v248 offset:35840
	ds_read_b128 v[180:183], v248 offset:36864
	ds_read_b128 v[184:187], v248 offset:37888
	ds_read_b128 v[188:191], v248 offset:38912
	ds_read_b128 v[214:217], v248 offset:39936
	s_mov_b32 m0, s43
	s_nop 0
	global_load_lds_dwordx4 v204, s[100:101]
	s_mov_b32 m0, s44
	s_nop 0
	global_load_lds_dwordx4 v206, s[100:101]
	s_waitcnt vmcnt(8)
	s_waitcnt lgkmcnt(0)
	s_setprio 2
	s_barrier
	v_mfma_f32_16x16x32_bf16 v[152:155], v[120:123], v[164:167], v[152:155]
	v_mfma_f32_16x16x32_bf16 v[148:151], v[132:135], v[164:167], v[148:151]
	v_mfma_f32_16x16x32_bf16 v[108:111], v[120:123], v[172:175], v[108:111]
	v_mfma_f32_16x16x32_bf16 v[104:107], v[132:135], v[172:175], v[104:107]
	v_mfma_f32_16x16x32_bf16 v[92:95], v[120:123], v[180:183], v[92:95]
	v_mfma_f32_16x16x32_bf16 v[88:91], v[132:135], v[180:183], v[88:91]
	v_mfma_f32_16x16x32_bf16 v[76:79], v[120:123], v[188:191], v[76:79]
	v_mfma_f32_16x16x32_bf16 v[72:75], v[132:135], v[188:191], v[72:75]
	v_mfma_f32_16x16x32_bf16 v[152:155], v[128:131], v[168:171], v[152:155]
	v_mfma_f32_16x16x32_bf16 v[148:151], v[136:139], v[168:171], v[148:151]
	v_mfma_f32_16x16x32_bf16 v[108:111], v[128:131], v[176:179], v[108:111]
	v_mfma_f32_16x16x32_bf16 v[104:107], v[136:139], v[176:179], v[104:107]
	v_mfma_f32_16x16x32_bf16 v[92:95], v[128:131], v[184:187], v[92:95]
	v_mfma_f32_16x16x32_bf16 v[88:91], v[136:139], v[184:187], v[88:91]
	v_mfma_f32_16x16x32_bf16 v[76:79], v[128:131], v[214:217], v[76:79]
	v_mfma_f32_16x16x32_bf16 v[72:75], v[136:139], v[214:217], v[72:75]
	v_mfma_f32_16x16x32_bf16 v[124:127], v[140:143], v[164:167], v[124:127]
	v_mfma_f32_16x16x32_bf16 v[112:115], v[156:159], v[164:167], v[112:115]
	v_mfma_f32_16x16x32_bf16 v[100:103], v[140:143], v[172:175], v[100:103]
	v_mfma_f32_16x16x32_bf16 v[96:99], v[156:159], v[172:175], v[96:99]
	v_mfma_f32_16x16x32_bf16 v[84:87], v[140:143], v[180:183], v[84:87]
	v_mfma_f32_16x16x32_bf16 v[80:83], v[156:159], v[180:183], v[80:83]
	v_mfma_f32_16x16x32_bf16 v[68:71], v[140:143], v[188:191], v[68:71]
	v_mfma_f32_16x16x32_bf16 v[64:67], v[156:159], v[188:191], v[64:67]
	v_mfma_f32_16x16x32_bf16 v[124:127], v[144:147], v[168:171], v[124:127]
	v_mfma_f32_16x16x32_bf16 v[112:115], v[160:163], v[168:171], v[112:115]
	v_mfma_f32_16x16x32_bf16 v[100:103], v[144:147], v[176:179], v[100:103]
	v_mfma_f32_16x16x32_bf16 v[96:99], v[160:163], v[176:179], v[96:99]
	s_setprio 3
	s_barrier
; #define PG8_STAGE(bufoff, gbase, voff) do { _Pragma("unroll") for (int _i = 0; _i < 2; ++_i) \
;         __builtin_amdgcn_global_load_lds((const unsigned*)((const char*)(gbase) + (voff)[_i]), (PG8_LAS unsigned*)(lds + (bufoff) + ldsw + _i * 8192), 16, 0, 0); } while (0)
; #define PG8_LDA(dst, b, h) do { _Pragma("unroll") for (int m = 0; m < 4; ++m) _Pragma("unroll") for (int k = 0; k < 2; ++k) dst[m][k] = *(const PG8_LAS bf16x8*)(lds + PG8_SA(b, h) + aoff + m * 2048 + k * 1024); } while (0)
; #define PG8_MMA(ai, bj, At, Bt) do { __builtin_amdgcn_s_setprio(1); _Pragma("unroll") for (int m = 0; m < 4; ++m) _Pragma("unroll") for (int n = 0; n < 2; ++n) _Pragma("unroll") for (int k = 0; k < 2; ++k) \
;         acc[ai][bj][m][n] = __builtin_amdgcn_mfma_f32_16x16x32_bf16(Bt[n][k], At[m][k], acc[ai][bj][m][n], 0, 0, 0); __builtin_amdgcn_s_setprio(0); } while (0)
; #define PG8_WAIT_V(n) asm volatile("s_waitcnt vmcnt(" #n ")" ::: "memory")
; #define PG8_WAIT_L(n) asm volatile("s_waitcnt lgkmcnt(" #n ")" ::: "memory")
; #define PG8_BAR __builtin_amdgcn_s_barrier()
; #define PG8_SCHED __builtin_amdgcn_sched_barrier(0)
; template <class Epi, class Sched, bool ALIGN_EPI = false, bool SP2 = false>
; __device__ __forceinline__ void gemm_phase(PG8_LAS unsigned char* lds, const Gemm g, const Sched& S, const Epi& E) {
;     ...
;         for (int t = 0; t < nt; t += 2) {
;     ...
;             PG8_STAGE(PG8_SB(1, 0), b3, voffB); PG8_STAGE(PG8_SB(1, 1), b3 + hstep, voffB); PG8_STAGE(PG8_SA(1, 0), a3, voffA); PG8_SCHED; PG8_LDA(At, 1, 1);
;             PG8_WAIT_V(8); PG8_WAIT_L(0); PG8_BAR; PG8_MMA(1, 0, At, B0); PG8_MMA(1, 1, At, B1); PG8_BAR; PG8_SCHED;
	v_mfma_f32_16x16x32_bf16 v[84:87], v[144:147], v[184:187], v[84:87]
	v_mfma_f32_16x16x32_bf16 v[80:83], v[160:163], v[184:187], v[80:83]
	v_mfma_f32_16x16x32_bf16 v[68:71], v[144:147], v[214:217], v[68:71]
	v_mfma_f32_16x16x32_bf16 v[64:67], v[160:163], v[214:217], v[64:67]
	s_setprio 0
	ds_read_b128 v[164:167], v248 offset:49152
	ds_read_b128 v[168:171], v248 offset:50176
	ds_read_b128 v[172:175], v248 offset:51200
	ds_read_b128 v[176:179], v248 offset:52224
	ds_read_b128 v[180:183], v248 offset:53248
	ds_read_b128 v[184:187], v248 offset:54272
	ds_read_b128 v[188:191], v248 offset:55296
	ds_read_b128 v[214:217], v248 offset:56320
	s_add_u32 s100, s28, 0x80
	s_addc_u32 s101, s29, 0
	s_add_u32 s28, s28, 0x100080
	s_addc_u32 s29, s29, 0
	s_add_u32 s98, s98, 0x80
	s_addc_u32 s99, s99, 0
	s_add_i32 m0, s30, s39
	s_nop 0
	global_load_lds_dwordx4 v194, s[100:101]
	s_add_i32 m0, m0, 0x2000
	s_nop 0
	global_load_lds_dwordx4 v208, s[100:101]
	s_add_i32 m0, s31, s39
	s_nop 0
	global_load_lds_dwordx4 v194, s[28:29]
	s_add_i32 m0, m0, 0x2000
	s_nop 0
	global_load_lds_dwordx4 v208, s[28:29]
	s_mov_b32 m0, s46
	s_nop 0
	global_load_lds_dwordx4 v204, s[98:99]
	s_mov_b32 m0, s48
	s_nop 0
	global_load_lds_dwordx4 v206, s[98:99]
	s_waitcnt vmcnt(8)
	s_waitcnt lgkmcnt(0)
	s_setprio 2
	s_barrier
	v_mfma_f32_16x16x32_bf16 v[60:63], v[120:123], v[164:167], v[60:63]
	v_mfma_f32_16x16x32_bf16 v[56:59], v[132:135], v[164:167], v[56:59]
	v_mfma_f32_16x16x32_bf16 v[44:47], v[120:123], v[172:175], v[44:47]
	v_mfma_f32_16x16x32_bf16 v[40:43], v[132:135], v[172:175], v[40:43]
	v_mfma_f32_16x16x32_bf16 v[28:31], v[120:123], v[180:183], v[28:31]
	v_mfma_f32_16x16x32_bf16 v[24:27], v[132:135], v[180:183], v[24:27]
	v_mfma_f32_16x16x32_bf16 v[12:15], v[120:123], v[188:191], v[12:15]
	v_mfma_f32_16x16x32_bf16 v[8:11], v[132:135], v[188:191], v[8:11]
	v_mfma_f32_16x16x32_bf16 v[60:63], v[128:131], v[168:171], v[60:63]
	v_mfma_f32_16x16x32_bf16 v[56:59], v[136:139], v[168:171], v[56:59]
	v_mfma_f32_16x16x32_bf16 v[44:47], v[128:131], v[176:179], v[44:47]
	v_mfma_f32_16x16x32_bf16 v[40:43], v[136:139], v[176:179], v[40:43]
	v_mfma_f32_16x16x32_bf16 v[28:31], v[128:131], v[184:187], v[28:31]
	v_mfma_f32_16x16x32_bf16 v[24:27], v[136:139], v[184:187], v[24:27]
	v_mfma_f32_16x16x32_bf16 v[12:15], v[128:131], v[214:217], v[12:15]
	v_mfma_f32_16x16x32_bf16 v[8:11], v[136:139], v[214:217], v[8:11]
	v_mfma_f32_16x16x32_bf16 v[52:55], v[140:143], v[164:167], v[52:55]
	v_mfma_f32_16x16x32_bf16 v[48:51], v[156:159], v[164:167], v[48:51]
	v_mfma_f32_16x16x32_bf16 v[36:39], v[140:143], v[172:175], v[36:39]
	v_mfma_f32_16x16x32_bf16 v[32:35], v[156:159], v[172:175], v[32:35]
	v_mfma_f32_16x16x32_bf16 v[20:23], v[140:143], v[180:183], v[20:23]
	v_mfma_f32_16x16x32_bf16 v[16:19], v[156:159], v[180:183], v[16:19]
	v_mfma_f32_16x16x32_bf16 v[4:7], v[140:143], v[188:191], v[4:7]
	v_mfma_f32_16x16x32_bf16 v[0:3], v[156:159], v[188:191], v[0:3]
	v_mfma_f32_16x16x32_bf16 v[52:55], v[144:147], v[168:171], v[52:55]
	v_mfma_f32_16x16x32_bf16 v[48:51], v[160:163], v[168:171], v[48:51]
	v_mfma_f32_16x16x32_bf16 v[36:39], v[144:147], v[176:179], v[36:39]
	v_mfma_f32_16x16x32_bf16 v[32:35], v[160:163], v[176:179], v[32:35]
	s_setprio 3
	s_barrier
	v_mfma_f32_16x16x32_bf16 v[20:23], v[144:147], v[184:187], v[20:23]
	v_mfma_f32_16x16x32_bf16 v[16:19], v[160:163], v[184:187], v[16:19]
	v_mfma_f32_16x16x32_bf16 v[4:7], v[144:147], v[214:217], v[4:7]
	v_mfma_f32_16x16x32_bf16 v[0:3], v[160:163], v[214:217], v[0:3]
	s_setprio 0
	s_add_i32 s56, s56, 2
	s_add_u32 s40, s40, 0x100
	s_addc_u32 s41, s41, 0
	s_cmp_gt_u32 s56, 61
	s_cbranch_scc0 .LBB0_965
	s_and_b64 vcc, exec, s[10:11]
	s_cbranch_vccz .LBB0_968
	s_barrier

; #define PG8_STAGE(bufoff, gbase, voff) do { _Pragma("unroll") for (int _i = 0; _i < 2; ++_i) \
;         __builtin_amdgcn_global_load_lds((const unsigned*)((const char*)(gbase) + (voff)[_i]), (PG8_LAS unsigned*)(lds + (bufoff) + ldsw + _i * 8192), 16, 0, 0); } while (0)
; #define PG8_LDA(dst, b, h) do { _Pragma("unroll") for (int m = 0; m < 4; ++m) _Pragma("unroll") for (int k = 0; k < 2; ++k) dst[m][k] = *(const PG8_LAS bf16x8*)(lds + PG8_SA(b, h) + aoff + m * 2048 + k * 1024); } while (0)
; #define PG8_LDB(dst, b, h) do { _Pragma("unroll") for (int n = 0; n < 2; ++n) _Pragma("unroll") for (int k = 0; k < 2; ++k) dst[n][k] = *(const PG8_LAS bf16x8*)(lds + PG8_SB(b, h) + boff + n * 2048 + k * 1024); } while (0)
; #define PG8_MMA(ai, bj, At, Bt) do { __builtin_amdgcn_s_setprio(1); _Pragma("unroll") for (int m = 0; m < 4; ++m) _Pragma("unroll") for (int n = 0; n < 2; ++n) _Pragma("unroll") for (int k = 0; k < 2; ++k) \
;         acc[ai][bj][m][n] = __builtin_amdgcn_mfma_f32_16x16x32_bf16(Bt[n][k], At[m][k], acc[ai][bj][m][n], 0, 0, 0); __builtin_amdgcn_s_setprio(0); } while (0)
; #define PG8_WAIT_L(n) asm volatile("s_waitcnt lgkmcnt(" #n ")" ::: "memory")
; #define PG8_WAIT_V8_UNLESS(flag) asm volatile("s_cmp_lg_i32 %0, 0\n\ts_cbranch_scc1 .Lpg8rx%=\n\ts_waitcnt vmcnt(8)\n.Lpg8rx%=:" :: "s"(__builtin_amdgcn_readfirstlane(flag)) : "scc", "memory")
; #define PG8_BAR __builtin_amdgcn_s_barrier()
; #define PG8_SCHED __builtin_amdgcn_sched_barrier(0)
; template <class Epi, class Sched, bool ALIGN_EPI = false, bool SP2 = false>
; __device__ __forceinline__ void gemm_phase(PG8_LAS unsigned char* lds, const Gemm g, const Sched& S, const Epi& E) {
;     ...
;             PG8_STAGE(PG8_SA(1, 1), a1 + hstep, voffA); PG8_SCHED; PG8_LDB(B0, 0, 0); PG8_LDB(B1, 0, 1); PG8_SCHED; PG8_LDA(At, 0, 0);
;             PG8_WAIT_V8_UNLESS(rx); PG8_WAIT_L(0); PG8_BAR; PG8_MMA(0, 0, At, B0); PG8_MMA(0, 1, At, B1); PG8_BAR; PG8_SCHED;
;             PG8_STAGE(PG8_SB(0, 0), b2, voffB); PG8_STAGE(PG8_SB(0, 1), b2 + hstep, voffB); PG8_STAGE(PG8_SA(0, 0), a2, voffA); PG8_SCHED; PG8_LDA(At, 0, 1);
;             PG8_WAIT_V8_UNLESS(rx); PG8_WAIT_L(0); PG8_BAR; PG8_MMA(1, 0, At, B0); PG8_MMA(1, 1, At, B1); PG8_BAR; PG8_SCHED;
.Lpg8rx8:
	s_waitcnt lgkmcnt(0)
	s_setprio 2
	s_barrier
	v_mfma_f32_16x16x32_bf16 v[120:123], v[140:143], v[172:175], v[120:123]
	v_mfma_f32_16x16x32_bf16 v[124:127], v[148:151], v[172:175], v[124:127]
	v_mfma_f32_16x16x32_bf16 v[108:111], v[140:143], v[180:183], v[108:111]
	v_mfma_f32_16x16x32_bf16 v[104:107], v[148:151], v[180:183], v[104:107]
	v_mfma_f32_16x16x32_bf16 v[92:95], v[140:143], v[188:191], v[92:95]
	v_mfma_f32_16x16x32_bf16 v[88:91], v[148:151], v[188:191], v[88:91]
	v_mfma_f32_16x16x32_bf16 v[76:79], v[140:143], v[208:211], v[76:79]
	v_mfma_f32_16x16x32_bf16 v[72:75], v[148:151], v[208:211], v[72:75]
	v_mfma_f32_16x16x32_bf16 v[120:123], v[144:147], v[176:179], v[120:123]
	v_mfma_f32_16x16x32_bf16 v[124:127], v[152:155], v[176:179], v[124:127]
	v_mfma_f32_16x16x32_bf16 v[108:111], v[144:147], v[184:187], v[108:111]
	v_mfma_f32_16x16x32_bf16 v[104:107], v[152:155], v[184:187], v[104:107]
	v_mfma_f32_16x16x32_bf16 v[92:95], v[144:147], v[204:207], v[92:95]
	v_mfma_f32_16x16x32_bf16 v[88:91], v[152:155], v[204:207], v[88:91]
	v_mfma_f32_16x16x32_bf16 v[76:79], v[144:147], v[212:215], v[76:79]
	v_mfma_f32_16x16x32_bf16 v[72:75], v[152:155], v[212:215], v[72:75]
	v_mfma_f32_16x16x32_bf16 v[116:119], v[156:159], v[172:175], v[116:119]
	v_mfma_f32_16x16x32_bf16 v[112:115], v[164:167], v[172:175], v[112:115]
	v_mfma_f32_16x16x32_bf16 v[100:103], v[156:159], v[180:183], v[100:103]
	v_mfma_f32_16x16x32_bf16 v[96:99], v[164:167], v[180:183], v[96:99]
	v_mfma_f32_16x16x32_bf16 v[84:87], v[156:159], v[188:191], v[84:87]
	v_mfma_f32_16x16x32_bf16 v[80:83], v[164:167], v[188:191], v[80:83]
	v_mfma_f32_16x16x32_bf16 v[68:71], v[156:159], v[208:211], v[68:71]
	v_mfma_f32_16x16x32_bf16 v[64:67], v[164:167], v[208:211], v[64:67]
	v_mfma_f32_16x16x32_bf16 v[116:119], v[160:163], v[176:179], v[116:119]
	v_mfma_f32_16x16x32_bf16 v[112:115], v[168:171], v[176:179], v[112:115]
	v_mfma_f32_16x16x32_bf16 v[100:103], v[160:163], v[184:187], v[100:103]
	v_mfma_f32_16x16x32_bf16 v[96:99], v[168:171], v[184:187], v[96:99]
	s_setprio 3
	s_barrier
	v_mfma_f32_16x16x32_bf16 v[84:87], v[160:163], v[204:207], v[84:87]
	v_mfma_f32_16x16x32_bf16 v[80:83], v[168:171], v[204:207], v[80:83]
	v_mfma_f32_16x16x32_bf16 v[68:71], v[160:163], v[212:215], v[68:71]
	v_mfma_f32_16x16x32_bf16 v[64:67], v[168:171], v[212:215], v[64:67]
	s_setprio 0
	s_add_i32 s63, s63, s34
	v_lshl_add_u64 v[216:217], s[66:67], 0, v[194:195]
	s_mov_b32 m0, s63
	v_lshl_add_u64 v[218:219], s[66:67], 0, v[132:133]
	global_load_lds_dwordx4 v[216:217], off
	s_add_i32 m0, s63, 0x2000
	s_add_u32 s66, s66, s8
	s_addc_u32 s67, s67, s9
	s_add_i32 s63, s65, s34
	global_load_lds_dwordx4 v[218:219], off
	v_lshl_add_u64 v[220:221], s[66:67], 0, v[194:195]
	s_mov_b32 m0, s63
	v_lshl_add_u64 v[222:223], s[66:67], 0, v[132:133]
	global_load_lds_dwordx4 v[220:221], off
	s_add_i32 m0, s63, 0x2000
	v_lshl_add_u64 v[224:225], s[24:25], 0, v[128:129]
	global_load_lds_dwordx4 v[222:223], off
	s_mov_b32 m0, s43
	v_lshl_add_u64 v[226:227], s[24:25], 0, v[130:131]
	global_load_lds_dwordx4 v[224:225], off
	s_mov_b32 m0, s44
	s_nop 0
	global_load_lds_dwordx4 v[226:227], off
	ds_read_b128 v[172:175], v139 offset:16384
	ds_read_b128 v[176:179], v139 offset:17408
	ds_read_b128 v[180:183], v139 offset:18432
	ds_read_b128 v[184:187], v139 offset:19456
	ds_read_b128 v[188:191], v139 offset:20480
	ds_read_b128 v[204:207], v139 offset:21504
	ds_read_b128 v[208:211], v139 offset:22528
	ds_read_b128 v[212:215], v139 offset:23552
	s_cmp_lg_i32 s73, 0
	s_cbranch_scc1 .Lpg8rx9
	s_waitcnt vmcnt(8)
.Lpg8rx9:
	s_waitcnt lgkmcnt(0)
	s_setprio 2
	s_barrier
	v_mfma_f32_16x16x32_bf16 v[60:63], v[140:143], v[172:175], v[60:63]
	v_mfma_f32_16x16x32_bf16 v[56:59], v[148:151], v[172:175], v[56:59]
	v_mfma_f32_16x16x32_bf16 v[44:47], v[140:143], v[180:183], v[44:47]
	v_mfma_f32_16x16x32_bf16 v[40:43], v[148:151], v[180:183], v[40:43]
	v_mfma_f32_16x16x32_bf16 v[28:31], v[140:143], v[188:191], v[28:31]
	v_mfma_f32_16x16x32_bf16 v[24:27], v[148:151], v[188:191], v[24:27]
	v_mfma_f32_16x16x32_bf16 v[12:15], v[140:143], v[208:211], v[12:15]
	v_mfma_f32_16x16x32_bf16 v[8:11], v[148:151], v[208:211], v[8:11]
	v_mfma_f32_16x16x32_bf16 v[60:63], v[144:147], v[176:179], v[60:63]
	v_mfma_f32_16x16x32_bf16 v[56:59], v[152:155], v[176:179], v[56:59]
	v_mfma_f32_16x16x32_bf16 v[44:47], v[144:147], v[184:187], v[44:47]
	v_mfma_f32_16x16x32_bf16 v[40:43], v[152:155], v[184:187], v[40:43]
	v_mfma_f32_16x16x32_bf16 v[28:31], v[144:147], v[204:207], v[28:31]
	v_mfma_f32_16x16x32_bf16 v[24:27], v[152:155], v[204:207], v[24:27]
	v_mfma_f32_16x16x32_bf16 v[12:15], v[144:147], v[212:215], v[12:15]
	v_mfma_f32_16x16x32_bf16 v[8:11], v[152:155], v[212:215], v[8:11]
	v_mfma_f32_16x16x32_bf16 v[52:55], v[156:159], v[172:175], v[52:55]
	v_mfma_f32_16x16x32_bf16 v[48:51], v[164:167], v[172:175], v[48:51]
	v_mfma_f32_16x16x32_bf16 v[36:39], v[156:159], v[180:183], v[36:39]
	v_mfma_f32_16x16x32_bf16 v[32:35], v[164:167], v[180:183], v[32:35]
	v_mfma_f32_16x16x32_bf16 v[20:23], v[156:159], v[188:191], v[20:23]
	v_mfma_f32_16x16x32_bf16 v[16:19], v[164:167], v[188:191], v[16:19]
	v_mfma_f32_16x16x32_bf16 v[4:7], v[156:159], v[208:211], v[4:7]
	v_mfma_f32_16x16x32_bf16 v[0:3], v[164:167], v[208:211], v[0:3]
	v_mfma_f32_16x16x32_bf16 v[52:55], v[160:163], v[176:179], v[52:55]
	v_mfma_f32_16x16x32_bf16 v[48:51], v[168:171], v[176:179], v[48:51]
	v_mfma_f32_16x16x32_bf16 v[36:39], v[160:163], v[184:187], v[36:39]
	v_mfma_f32_16x16x32_bf16 v[32:35], v[168:171], v[184:187], v[32:35]
	s_setprio 3
	s_barrier
; #define PG8_STAGE(bufoff, gbase, voff) do { _Pragma("unroll") for (int _i = 0; _i < 2; ++_i) \
;         __builtin_amdgcn_global_load_lds((const unsigned*)((const char*)(gbase) + (voff)[_i]), (PG8_LAS unsigned*)(lds + (bufoff) + ldsw + _i * 8192), 16, 0, 0); } while (0)
; #define PG8_LDA(dst, b, h) do { _Pragma("unroll") for (int m = 0; m < 4; ++m) _Pragma("unroll") for (int k = 0; k < 2; ++k) dst[m][k] = *(const PG8_LAS bf16x8*)(lds + PG8_SA(b, h) + aoff + m * 2048 + k * 1024); } while (0)
; #define PG8_LDB(dst, b, h) do { _Pragma("unroll") for (int n = 0; n < 2; ++n) _Pragma("unroll") for (int k = 0; k < 2; ++k) dst[n][k] = *(const PG8_LAS bf16x8*)(lds + PG8_SB(b, h) + boff + n * 2048 + k * 1024); } while (0)
; #define PG8_MMA(ai, bj, At, Bt) do { __builtin_amdgcn_s_setprio(1); _Pragma("unroll") for (int m = 0; m < 4; ++m) _Pragma("unroll") for (int n = 0; n < 2; ++n) _Pragma("unroll") for (int k = 0; k < 2; ++k) \
;         acc[ai][bj][m][n] = __builtin_amdgcn_mfma_f32_16x16x32_bf16(Bt[n][k], At[m][k], acc[ai][bj][m][n], 0, 0, 0); __builtin_amdgcn_s_setprio(0); } while (0)
; #define PG8_WAIT_V(n) asm volatile("s_waitcnt vmcnt(" #n ")" ::: "memory")
; #define PG8_WAIT_L(n) asm volatile("s_waitcnt lgkmcnt(" #n ")" ::: "memory")
; #define PG8_BAR __builtin_amdgcn_s_barrier()
; #define PG8_SCHED __builtin_amdgcn_sched_barrier(0)
; template <class Epi, class Sched, bool ALIGN_EPI = false, bool SP2 = false>
; __device__ __forceinline__ void gemm_phase(PG8_LAS unsigned char* lds, const Gemm g, const Sched& S, const Epi& E) {
;     ...
;             PG8_STAGE(PG8_SA(0, 1), a2 + hstep, voffA); PG8_SCHED; PG8_LDB(B0, 1, 0); PG8_LDB(B1, 1, 1); PG8_SCHED; PG8_LDA(At, 1, 0);
;             PG8_WAIT_V(8); PG8_WAIT_L(0); PG8_BAR; PG8_MMA(0, 0, At, B0); PG8_MMA(0, 1, At, B1); PG8_BAR; PG8_SCHED;
	v_mfma_f32_16x16x32_bf16 v[20:23], v[160:163], v[204:207], v[20:23]
	v_mfma_f32_16x16x32_bf16 v[16:19], v[168:171], v[204:207], v[16:19]
	v_mfma_f32_16x16x32_bf16 v[4:7], v[160:163], v[212:215], v[4:7]
	v_mfma_f32_16x16x32_bf16 v[0:3], v[168:171], v[212:215], v[0:3]
	s_setprio 0
	s_add_u32 s24, s24, s8
	s_addc_u32 s25, s25, s9
	s_mov_b32 m0, s46
	v_lshl_add_u64 v[140:141], s[24:25], 0, v[128:129]
	global_load_lds_dwordx4 v[140:141], off
	v_lshl_add_u64 v[140:141], s[24:25], 0, v[130:131]
	s_mov_b32 m0, s48
	s_nop 0
	global_load_lds_dwordx4 v[140:141], off
	s_add_i32 s24, 0, 0x18000
	s_add_i32 s25, 0, 0x1c000
	v_add_u32_e32 v152, s24, v138
	v_add_u32_e32 v168, s25, v138
	ds_read_b128 v[140:143], v152
	ds_read_b128 v[144:147], v152 offset:1024
	ds_read_b128 v[148:151], v152 offset:2048
	ds_read_b128 v[152:155], v152 offset:3072
	ds_read_b128 v[156:159], v168
	ds_read_b128 v[160:163], v168 offset:1024
	ds_read_b128 v[164:167], v168 offset:2048
	ds_read_b128 v[168:171], v168 offset:3072
	ds_read_b128 v[172:175], v139 offset:32768
	ds_read_b128 v[176:179], v139 offset:33792
	ds_read_b128 v[180:183], v139 offset:34816
	ds_read_b128 v[184:187], v139 offset:35840
	ds_read_b128 v[188:191], v139 offset:36864
	ds_read_b128 v[204:207], v139 offset:37888
	ds_read_b128 v[208:211], v139 offset:38912
	ds_read_b128 v[212:215], v139 offset:39936
	s_waitcnt vmcnt(8)
	s_waitcnt lgkmcnt(0)
	s_setprio 2
	s_barrier
	v_mfma_f32_16x16x32_bf16 v[120:123], v[140:143], v[172:175], v[120:123]
	v_mfma_f32_16x16x32_bf16 v[124:127], v[148:151], v[172:175], v[124:127]
	v_mfma_f32_16x16x32_bf16 v[108:111], v[140:143], v[180:183], v[108:111]
	v_mfma_f32_16x16x32_bf16 v[104:107], v[148:151], v[180:183], v[104:107]
	v_mfma_f32_16x16x32_bf16 v[92:95], v[140:143], v[188:191], v[92:95]
	v_mfma_f32_16x16x32_bf16 v[88:91], v[148:151], v[188:191], v[88:91]
	v_mfma_f32_16x16x32_bf16 v[76:79], v[140:143], v[208:211], v[76:79]
	v_mfma_f32_16x16x32_bf16 v[72:75], v[148:151], v[208:211], v[72:75]
	v_mfma_f32_16x16x32_bf16 v[120:123], v[144:147], v[176:179], v[120:123]
	v_mfma_f32_16x16x32_bf16 v[124:127], v[152:155], v[176:179], v[124:127]
	v_mfma_f32_16x16x32_bf16 v[108:111], v[144:147], v[184:187], v[108:111]
	v_mfma_f32_16x16x32_bf16 v[104:107], v[152:155], v[184:187], v[104:107]
	v_mfma_f32_16x16x32_bf16 v[92:95], v[144:147], v[204:207], v[92:95]
	v_mfma_f32_16x16x32_bf16 v[88:91], v[152:155], v[204:207], v[88:91]
	v_mfma_f32_16x16x32_bf16 v[76:79], v[144:147], v[212:215], v[76:79]
	v_mfma_f32_16x16x32_bf16 v[72:75], v[152:155], v[212:215], v[72:75]
	v_mfma_f32_16x16x32_bf16 v[116:119], v[156:159], v[172:175], v[116:119]
	v_mfma_f32_16x16x32_bf16 v[112:115], v[164:167], v[172:175], v[112:115]
	v_mfma_f32_16x16x32_bf16 v[100:103], v[156:159], v[180:183], v[100:103]
	v_mfma_f32_16x16x32_bf16 v[96:99], v[164:167], v[180:183], v[96:99]
	v_mfma_f32_16x16x32_bf16 v[84:87], v[156:159], v[188:191], v[84:87]
	v_mfma_f32_16x16x32_bf16 v[80:83], v[164:167], v[188:191], v[80:83]
	v_mfma_f32_16x16x32_bf16 v[68:71], v[156:159], v[208:211], v[68:71]
	v_mfma_f32_16x16x32_bf16 v[64:67], v[164:167], v[208:211], v[64:67]
	v_mfma_f32_16x16x32_bf16 v[116:119], v[160:163], v[176:179], v[116:119]
	v_mfma_f32_16x16x32_bf16 v[112:115], v[168:171], v[176:179], v[112:115]
	v_mfma_f32_16x16x32_bf16 v[100:103], v[160:163], v[184:187], v[100:103]
	v_mfma_f32_16x16x32_bf16 v[96:99], v[168:171], v[184:187], v[96:99]
	s_setprio 3
	s_barrier
; #define PG8_STAGE(bufoff, gbase, voff) do { _Pragma("unroll") for (int _i = 0; _i < 2; ++_i) \
;         __builtin_amdgcn_global_load_lds((const unsigned*)((const char*)(gbase) + (voff)[_i]), (PG8_LAS unsigned*)(lds + (bufoff) + ldsw + _i * 8192), 16, 0, 0); } while (0)
; #define PG8_LDA(dst, b, h) do { _Pragma("unroll") for (int m = 0; m < 4; ++m) _Pragma("unroll") for (int k = 0; k < 2; ++k) dst[m][k] = *(const PG8_LAS bf16x8*)(lds + PG8_SA(b, h) + aoff + m * 2048 + k * 1024); } while (0)
; #define PG8_MMA(ai, bj, At, Bt) do { __builtin_amdgcn_s_setprio(1); _Pragma("unroll") for (int m = 0; m < 4; ++m) _Pragma("unroll") for (int n = 0; n < 2; ++n) _Pragma("unroll") for (int k = 0; k < 2; ++k) \
;         acc[ai][bj][m][n] = __builtin_amdgcn_mfma_f32_16x16x32_bf16(Bt[n][k], At[m][k], acc[ai][bj][m][n], 0, 0, 0); __builtin_amdgcn_s_setprio(0); } while (0)
; #define PG8_WAIT_V(n) asm volatile("s_waitcnt vmcnt(" #n ")" ::: "memory")
; #define PG8_WAIT_L(n) asm volatile("s_waitcnt lgkmcnt(" #n ")" ::: "memory")
; #define PG8_BAR __builtin_amdgcn_s_barrier()
; #define PG8_SCHED __builtin_amdgcn_sched_barrier(0)
; template <class Epi, class Sched, bool ALIGN_EPI = false, bool SP2 = false>
; __device__ __forceinline__ void gemm_phase(PG8_LAS unsigned char* lds, const Gemm g, const Sched& S, const Epi& E) {
;     ...
;         for (int t = 0; t < nt; t += 2) {
;     ...
;             PG8_STAGE(PG8_SB(1, 0), b3, voffB); PG8_STAGE(PG8_SB(1, 1), b3 + hstep, voffB); PG8_STAGE(PG8_SA(1, 0), a3, voffA); PG8_SCHED; PG8_LDA(At, 1, 1);
;             PG8_WAIT_V(8); PG8_WAIT_L(0); PG8_BAR; PG8_MMA(1, 0, At, B0); PG8_MMA(1, 1, At, B1); PG8_BAR; PG8_SCHED;
	v_mfma_f32_16x16x32_bf16 v[84:87], v[160:163], v[204:207], v[84:87]
	v_mfma_f32_16x16x32_bf16 v[80:83], v[168:171], v[204:207], v[80:83]
	v_mfma_f32_16x16x32_bf16 v[68:71], v[160:163], v[212:215], v[68:71]
	v_mfma_f32_16x16x32_bf16 v[64:67], v[168:171], v[212:215], v[64:67]
	s_setprio 0
	s_add_i32 s24, s24, s34
	v_lshl_add_u64 v[172:173], v[216:217], 0, s[74:75]
	s_mov_b32 m0, s24
	s_nop 0
	global_load_lds_dwordx4 v[172:173], off
	v_lshl_add_u64 v[172:173], v[218:219], 0, s[74:75]
	s_add_i32 m0, s24, 0x2000
	s_add_i32 s24, s25, s34
	global_load_lds_dwordx4 v[172:173], off
	v_lshl_add_u64 v[172:173], v[220:221], 0, s[74:75]
	s_mov_b32 m0, s24
	s_nop 0
	global_load_lds_dwordx4 v[172:173], off
	v_lshl_add_u64 v[172:173], v[222:223], 0, s[74:75]
	s_add_i32 m0, s24, 0x2000
	s_nop 0
	global_load_lds_dwordx4 v[172:173], off
	v_lshl_add_u64 v[172:173], v[224:225], 0, s[74:75]
	s_mov_b32 m0, s53
	s_nop 0
	global_load_lds_dwordx4 v[172:173], off
	v_lshl_add_u64 v[172:173], v[226:227], 0, s[74:75]
	s_mov_b32 m0, s54
	s_nop 0
	global_load_lds_dwordx4 v[172:173], off
	ds_read_b128 v[172:175], v139 offset:49152
	ds_read_b128 v[176:179], v139 offset:50176
	ds_read_b128 v[180:183], v139 offset:51200
	ds_read_b128 v[184:187], v139 offset:52224
	ds_read_b128 v[188:191], v139 offset:53248
	ds_read_b128 v[204:207], v139 offset:54272
	ds_read_b128 v[208:211], v139 offset:55296
	ds_read_b128 v[212:215], v139 offset:56320
	s_waitcnt vmcnt(8)
	s_waitcnt lgkmcnt(0)
	s_setprio 2
	s_barrier
	v_mfma_f32_16x16x32_bf16 v[60:63], v[140:143], v[172:175], v[60:63]
	v_mfma_f32_16x16x32_bf16 v[56:59], v[148:151], v[172:175], v[56:59]
	v_mfma_f32_16x16x32_bf16 v[44:47], v[140:143], v[180:183], v[44:47]
	v_mfma_f32_16x16x32_bf16 v[40:43], v[148:151], v[180:183], v[40:43]
	v_mfma_f32_16x16x32_bf16 v[28:31], v[140:143], v[188:191], v[28:31]
	v_mfma_f32_16x16x32_bf16 v[24:27], v[148:151], v[188:191], v[24:27]
	v_mfma_f32_16x16x32_bf16 v[12:15], v[140:143], v[208:211], v[12:15]
	v_mfma_f32_16x16x32_bf16 v[8:11], v[148:151], v[208:211], v[8:11]
	v_mfma_f32_16x16x32_bf16 v[60:63], v[144:147], v[176:179], v[60:63]
	v_mfma_f32_16x16x32_bf16 v[56:59], v[152:155], v[176:179], v[56:59]
	v_mfma_f32_16x16x32_bf16 v[44:47], v[144:147], v[184:187], v[44:47]
	v_mfma_f32_16x16x32_bf16 v[40:43], v[152:155], v[184:187], v[40:43]
	v_mfma_f32_16x16x32_bf16 v[28:31], v[144:147], v[204:207], v[28:31]
	v_mfma_f32_16x16x32_bf16 v[24:27], v[152:155], v[204:207], v[24:27]
	v_mfma_f32_16x16x32_bf16 v[12:15], v[144:147], v[212:215], v[12:15]
	v_mfma_f32_16x16x32_bf16 v[8:11], v[152:155], v[212:215], v[8:11]
	v_mfma_f32_16x16x32_bf16 v[52:55], v[156:159], v[172:175], v[52:55]
	v_mfma_f32_16x16x32_bf16 v[48:51], v[164:167], v[172:175], v[48:51]
	v_mfma_f32_16x16x32_bf16 v[36:39], v[156:159], v[180:183], v[36:39]
	v_mfma_f32_16x16x32_bf16 v[32:35], v[164:167], v[180:183], v[32:35]
	v_mfma_f32_16x16x32_bf16 v[20:23], v[156:159], v[188:191], v[20:23]
	v_mfma_f32_16x16x32_bf16 v[16:19], v[164:167], v[188:191], v[16:19]
	v_mfma_f32_16x16x32_bf16 v[4:7], v[156:159], v[208:211], v[4:7]
	v_mfma_f32_16x16x32_bf16 v[0:3], v[164:167], v[208:211], v[0:3]
	v_mfma_f32_16x16x32_bf16 v[52:55], v[160:163], v[176:179], v[52:55]
	v_mfma_f32_16x16x32_bf16 v[48:51], v[168:171], v[176:179], v[48:51]
	v_mfma_f32_16x16x32_bf16 v[36:39], v[160:163], v[184:187], v[36:39]
	v_mfma_f32_16x16x32_bf16 v[32:35], v[168:171], v[184:187], v[32:35]
	s_setprio 3
	s_barrier
	v_mfma_f32_16x16x32_bf16 v[20:23], v[160:163], v[204:207], v[20:23]
	v_mfma_f32_16x16x32_bf16 v[16:19], v[168:171], v[204:207], v[16:19]
	v_mfma_f32_16x16x32_bf16 v[4:7], v[160:163], v[212:215], v[4:7]
	v_mfma_f32_16x16x32_bf16 v[0:3], v[168:171], v[212:215], v[0:3]
	s_setprio 0
	s_add_u32 s22, s22, 0x100
	s_addc_u32 s23, s23, 0
	s_add_u32 s60, s60, 0x100
	s_addc_u32 s61, s61, 0
	s_cmp_ge_i32 s62, s51
	s_mov_b32 s24, s62
	s_cbranch_scc0 .LBB0_1091

; #define PG8_STAGE(bufoff, gbase, voff) do { _Pragma("unroll") for (int _i = 0; _i < 2; ++_i) \
;         __builtin_amdgcn_global_load_lds((const unsigned*)((const char*)(gbase) + (voff)[_i]), (PG8_LAS unsigned*)(lds + (bufoff) + ldsw + _i * 8192), 16, 0, 0); } while (0)
; #define PG8_LDA(dst, b, h) do { _Pragma("unroll") for (int m = 0; m < 4; ++m) _Pragma("unroll") for (int k = 0; k < 2; ++k) dst[m][k] = *(const PG8_LAS bf16x8*)(lds + PG8_SA(b, h) + aoff + m * 2048 + k * 1024); } while (0)
; #define PG8_LDB(dst, b, h) do { _Pragma("unroll") for (int n = 0; n < 2; ++n) _Pragma("unroll") for (int k = 0; k < 2; ++k) dst[n][k] = *(const PG8_LAS bf16x8*)(lds + PG8_SB(b, h) + boff + n * 2048 + k * 1024); } while (0)
; #define PG8_MMA(ai, bj, At, Bt) do { __builtin_amdgcn_s_setprio(1); _Pragma("unroll") for (int m = 0; m < 4; ++m) _Pragma("unroll") for (int n = 0; n < 2; ++n) _Pragma("unroll") for (int k = 0; k < 2; ++k) \
;         acc[ai][bj][m][n] = __builtin_amdgcn_mfma_f32_16x16x32_bf16(Bt[n][k], At[m][k], acc[ai][bj][m][n], 0, 0, 0); __builtin_amdgcn_s_setprio(0); } while (0)
; #define PG8_WAIT_L(n) asm volatile("s_waitcnt lgkmcnt(" #n ")" ::: "memory")
; #define PG8_WAIT_V8_UNLESS(flag) asm volatile("s_cmp_lg_i32 %0, 0\n\ts_cbranch_scc1 .Lpg8rx%=\n\ts_waitcnt vmcnt(8)\n.Lpg8rx%=:" :: "s"(__builtin_amdgcn_readfirstlane(flag)) : "scc", "memory")
; #define PG8_BAR __builtin_amdgcn_s_barrier()
; #define PG8_SCHED __builtin_amdgcn_sched_barrier(0)
; template <class Epi, class Sched, bool ALIGN_EPI = false, bool SP2 = false>
; __device__ __forceinline__ void gemm_phase(PG8_LAS unsigned char* lds, const Gemm g, const Sched& S, const Epi& E) {
;     ...
;             PG8_STAGE(PG8_SA(1, 1), a1 + hstep, voffA); PG8_SCHED; PG8_LDB(B0, 0, 0); PG8_LDB(B1, 0, 1); PG8_SCHED; PG8_LDA(At, 0, 0);
;             PG8_WAIT_V8_UNLESS(rx); PG8_WAIT_L(0); PG8_BAR; PG8_MMA(0, 0, At, B0); PG8_MMA(0, 1, At, B1); PG8_BAR; PG8_SCHED;
;             PG8_STAGE(PG8_SB(0, 0), b2, voffB); PG8_STAGE(PG8_SB(0, 1), b2 + hstep, voffB); PG8_STAGE(PG8_SA(0, 0), a2, voffA); PG8_SCHED; PG8_LDA(At, 0, 1);
;             PG8_WAIT_V8_UNLESS(rx); PG8_WAIT_L(0); PG8_BAR; PG8_MMA(1, 0, At, B0); PG8_MMA(1, 1, At, B1); PG8_BAR; PG8_SCHED;
.Lpg8rx10:
	s_waitcnt lgkmcnt(0)
	s_setprio 2
	s_barrier
	v_mfma_f32_16x16x32_bf16 v[124:127], v[132:135], v[180:183], v[124:127]
	v_mfma_f32_16x16x32_bf16 v[120:123], v[140:143], v[180:183], v[120:123]
	v_mfma_f32_16x16x32_bf16 v[108:111], v[132:135], v[188:191], v[108:111]
	v_mfma_f32_16x16x32_bf16 v[104:107], v[140:143], v[188:191], v[104:107]
	v_mfma_f32_16x16x32_bf16 v[92:95], v[132:135], v[208:211], v[92:95]
	v_mfma_f32_16x16x32_bf16 v[88:91], v[140:143], v[208:211], v[88:91]
	v_mfma_f32_16x16x32_bf16 v[76:79], v[132:135], v[216:219], v[76:79]
	v_mfma_f32_16x16x32_bf16 v[72:75], v[140:143], v[216:219], v[72:75]
	v_mfma_f32_16x16x32_bf16 v[124:127], v[136:139], v[184:187], v[124:127]
	v_mfma_f32_16x16x32_bf16 v[120:123], v[144:147], v[184:187], v[120:123]
	v_mfma_f32_16x16x32_bf16 v[108:111], v[136:139], v[204:207], v[108:111]
	v_mfma_f32_16x16x32_bf16 v[104:107], v[144:147], v[204:207], v[104:107]
	v_mfma_f32_16x16x32_bf16 v[92:95], v[136:139], v[212:215], v[92:95]
	v_mfma_f32_16x16x32_bf16 v[88:91], v[144:147], v[212:215], v[88:91]
	v_mfma_f32_16x16x32_bf16 v[76:79], v[136:139], v[220:223], v[76:79]
	v_mfma_f32_16x16x32_bf16 v[72:75], v[144:147], v[220:223], v[72:75]
	v_mfma_f32_16x16x32_bf16 v[116:119], v[160:163], v[180:183], v[116:119]
	v_mfma_f32_16x16x32_bf16 v[112:115], v[168:171], v[180:183], v[112:115]
	v_mfma_f32_16x16x32_bf16 v[100:103], v[160:163], v[188:191], v[100:103]
	v_mfma_f32_16x16x32_bf16 v[96:99], v[168:171], v[188:191], v[96:99]
	v_mfma_f32_16x16x32_bf16 v[84:87], v[160:163], v[208:211], v[84:87]
	v_mfma_f32_16x16x32_bf16 v[80:83], v[168:171], v[208:211], v[80:83]
	v_mfma_f32_16x16x32_bf16 v[68:71], v[160:163], v[216:219], v[68:71]
	v_mfma_f32_16x16x32_bf16 v[64:67], v[168:171], v[216:219], v[64:67]
	v_mfma_f32_16x16x32_bf16 v[116:119], v[164:167], v[184:187], v[116:119]
	v_mfma_f32_16x16x32_bf16 v[112:115], v[176:179], v[184:187], v[112:115]
	v_mfma_f32_16x16x32_bf16 v[100:103], v[164:167], v[204:207], v[100:103]
	v_mfma_f32_16x16x32_bf16 v[96:99], v[176:179], v[204:207], v[96:99]
	s_setprio 3
	s_barrier
	v_mfma_f32_16x16x32_bf16 v[84:87], v[164:167], v[212:215], v[84:87]
	v_mfma_f32_16x16x32_bf16 v[80:83], v[176:179], v[212:215], v[80:83]
	v_mfma_f32_16x16x32_bf16 v[68:71], v[164:167], v[220:223], v[68:71]
	v_mfma_f32_16x16x32_bf16 v[64:67], v[176:179], v[220:223], v[64:67]
	s_setprio 0
	ds_read_b128 v[180:183], v175 offset:16384
	ds_read_b128 v[184:187], v175 offset:17408
	ds_read_b128 v[188:191], v175 offset:18432
	ds_read_b128 v[204:207], v175 offset:19456
	ds_read_b128 v[208:211], v175 offset:20480
	ds_read_b128 v[212:215], v175 offset:21504
	ds_read_b128 v[216:219], v175 offset:22528
	ds_read_b128 v[220:223], v175 offset:23552
	s_add_u32 s60, s28, 0x40000
	s_addc_u32 s61, s29, 0
	s_add_i32 m0, s65, s35
	s_nop 0
	global_load_lds_dwordx4 v150, s[28:29]
	s_add_i32 m0, m0, 0x2000
	s_nop 0
	global_load_lds_dwordx4 v154, s[28:29]
	s_add_i32 m0, s66, s35
	s_nop 0
	global_load_lds_dwordx4 v150, s[60:61]
	s_add_i32 m0, m0, 0x2000
	s_nop 0
	global_load_lds_dwordx4 v154, s[60:61]
	s_mov_b32 m0, s41
	s_nop 0
	global_load_lds_dwordx4 v148, s[30:31]
	s_mov_b32 m0, s48
	s_nop 0
	global_load_lds_dwordx4 v152, s[30:31]
	s_cmp_lg_i32 s67, 0
	s_cbranch_scc1 .Lpg8rx11
	s_waitcnt vmcnt(8)
.Lpg8rx11:
	s_waitcnt lgkmcnt(0)
	s_setprio 2
	s_barrier
	v_mfma_f32_16x16x32_bf16 v[60:63], v[132:135], v[180:183], v[60:63]
	v_mfma_f32_16x16x32_bf16 v[56:59], v[140:143], v[180:183], v[56:59]
	v_mfma_f32_16x16x32_bf16 v[44:47], v[132:135], v[188:191], v[44:47]
	v_mfma_f32_16x16x32_bf16 v[40:43], v[140:143], v[188:191], v[40:43]
	v_mfma_f32_16x16x32_bf16 v[28:31], v[132:135], v[208:211], v[28:31]
	v_mfma_f32_16x16x32_bf16 v[24:27], v[140:143], v[208:211], v[24:27]
	v_mfma_f32_16x16x32_bf16 v[12:15], v[132:135], v[216:219], v[12:15]
	v_mfma_f32_16x16x32_bf16 v[8:11], v[140:143], v[216:219], v[8:11]
	v_mfma_f32_16x16x32_bf16 v[60:63], v[136:139], v[184:187], v[60:63]
	v_mfma_f32_16x16x32_bf16 v[56:59], v[144:147], v[184:187], v[56:59]
	v_mfma_f32_16x16x32_bf16 v[44:47], v[136:139], v[204:207], v[44:47]
	v_mfma_f32_16x16x32_bf16 v[40:43], v[144:147], v[204:207], v[40:43]
	v_mfma_f32_16x16x32_bf16 v[28:31], v[136:139], v[212:215], v[28:31]
	v_mfma_f32_16x16x32_bf16 v[24:27], v[144:147], v[212:215], v[24:27]
	v_mfma_f32_16x16x32_bf16 v[12:15], v[136:139], v[220:223], v[12:15]
	v_mfma_f32_16x16x32_bf16 v[8:11], v[144:147], v[220:223], v[8:11]
	v_mfma_f32_16x16x32_bf16 v[52:55], v[160:163], v[180:183], v[52:55]
	v_mfma_f32_16x16x32_bf16 v[48:51], v[168:171], v[180:183], v[48:51]
	v_mfma_f32_16x16x32_bf16 v[36:39], v[160:163], v[188:191], v[36:39]
	v_mfma_f32_16x16x32_bf16 v[32:35], v[168:171], v[188:191], v[32:35]
	v_mfma_f32_16x16x32_bf16 v[20:23], v[160:163], v[208:211], v[20:23]
	v_mfma_f32_16x16x32_bf16 v[16:19], v[168:171], v[208:211], v[16:19]
	v_mfma_f32_16x16x32_bf16 v[4:7], v[160:163], v[216:219], v[4:7]
	v_mfma_f32_16x16x32_bf16 v[0:3], v[168:171], v[216:219], v[0:3]
	v_mfma_f32_16x16x32_bf16 v[52:55], v[164:167], v[184:187], v[52:55]
	v_mfma_f32_16x16x32_bf16 v[48:51], v[176:179], v[184:187], v[48:51]
	v_mfma_f32_16x16x32_bf16 v[36:39], v[164:167], v[204:207], v[36:39]
	v_mfma_f32_16x16x32_bf16 v[32:35], v[176:179], v[204:207], v[32:35]
	s_setprio 3
	s_barrier
; #define PG8_STAGE(bufoff, gbase, voff) do { _Pragma("unroll") for (int _i = 0; _i < 2; ++_i) \
;         __builtin_amdgcn_global_load_lds((const unsigned*)((const char*)(gbase) + (voff)[_i]), (PG8_LAS unsigned*)(lds + (bufoff) + ldsw + _i * 8192), 16, 0, 0); } while (0)
; #define PG8_LDA(dst, b, h) do { _Pragma("unroll") for (int m = 0; m < 4; ++m) _Pragma("unroll") for (int k = 0; k < 2; ++k) dst[m][k] = *(const PG8_LAS bf16x8*)(lds + PG8_SA(b, h) + aoff + m * 2048 + k * 1024); } while (0)
; #define PG8_LDB(dst, b, h) do { _Pragma("unroll") for (int n = 0; n < 2; ++n) _Pragma("unroll") for (int k = 0; k < 2; ++k) dst[n][k] = *(const PG8_LAS bf16x8*)(lds + PG8_SB(b, h) + boff + n * 2048 + k * 1024); } while (0)
; #define PG8_MMA(ai, bj, At, Bt) do { __builtin_amdgcn_s_setprio(1); _Pragma("unroll") for (int m = 0; m < 4; ++m) _Pragma("unroll") for (int n = 0; n < 2; ++n) _Pragma("unroll") for (int k = 0; k < 2; ++k) \
;         acc[ai][bj][m][n] = __builtin_amdgcn_mfma_f32_16x16x32_bf16(Bt[n][k], At[m][k], acc[ai][bj][m][n], 0, 0, 0); __builtin_amdgcn_s_setprio(0); } while (0)
; #define PG8_WAIT_V(n) asm volatile("s_waitcnt vmcnt(" #n ")" ::: "memory")
; #define PG8_WAIT_L(n) asm volatile("s_waitcnt lgkmcnt(" #n ")" ::: "memory")
; #define PG8_BAR __builtin_amdgcn_s_barrier()
; #define PG8_SCHED __builtin_amdgcn_sched_barrier(0)
; template <class Epi, class Sched, bool ALIGN_EPI = false, bool SP2 = false>
; __device__ __forceinline__ void gemm_phase(PG8_LAS unsigned char* lds, const Gemm g, const Sched& S, const Epi& E) {
;     ...
;             PG8_STAGE(PG8_SA(0, 1), a2 + hstep, voffA); PG8_SCHED; PG8_LDB(B0, 1, 0); PG8_LDB(B1, 1, 1); PG8_SCHED; PG8_LDA(At, 1, 0);
;             PG8_WAIT_V(8); PG8_WAIT_L(0); PG8_BAR; PG8_MMA(0, 0, At, B0); PG8_MMA(0, 1, At, B1); PG8_BAR; PG8_SCHED;
	v_mfma_f32_16x16x32_bf16 v[20:23], v[164:167], v[212:215], v[20:23]
	v_mfma_f32_16x16x32_bf16 v[16:19], v[176:179], v[212:215], v[16:19]
	v_mfma_f32_16x16x32_bf16 v[4:7], v[164:167], v[220:223], v[4:7]
	v_mfma_f32_16x16x32_bf16 v[0:3], v[176:179], v[220:223], v[0:3]
	s_setprio 0
	s_mov_b64 s[98:99], s[30:31]
	s_add_u32 s100, s30, 0x40000
	s_addc_u32 s101, s31, 0
	s_add_i32 s30, 0, 0x18000
	s_add_i32 s31, 0, 0x1c000
	v_add_u32_e32 v144, s30, v174
	v_add_u32_e32 v176, s31, v174
	ds_read_b128 v[132:135], v144
	ds_read_b128 v[136:139], v144 offset:1024
	ds_read_b128 v[140:143], v144 offset:2048
	ds_read_b128 v[144:147], v144 offset:3072
	ds_read_b128 v[160:163], v176
	ds_read_b128 v[164:167], v176 offset:1024
	ds_read_b128 v[168:171], v176 offset:2048
	ds_read_b128 v[176:179], v176 offset:3072
	ds_read_b128 v[180:183], v175 offset:32768
	ds_read_b128 v[184:187], v175 offset:33792
	ds_read_b128 v[188:191], v175 offset:34816
	ds_read_b128 v[204:207], v175 offset:35840
	ds_read_b128 v[208:211], v175 offset:36864
	ds_read_b128 v[212:215], v175 offset:37888
	ds_read_b128 v[216:219], v175 offset:38912
	ds_read_b128 v[220:223], v175 offset:39936
	s_mov_b32 m0, s50
	s_nop 0
	global_load_lds_dwordx4 v148, s[100:101]
	s_mov_b32 m0, s51
	s_nop 0
	global_load_lds_dwordx4 v152, s[100:101]
	s_waitcnt vmcnt(8)
	s_waitcnt lgkmcnt(0)
	s_setprio 2
	s_barrier
	v_mfma_f32_16x16x32_bf16 v[124:127], v[132:135], v[180:183], v[124:127]
	v_mfma_f32_16x16x32_bf16 v[120:123], v[140:143], v[180:183], v[120:123]
	v_mfma_f32_16x16x32_bf16 v[108:111], v[132:135], v[188:191], v[108:111]
	v_mfma_f32_16x16x32_bf16 v[104:107], v[140:143], v[188:191], v[104:107]
	v_mfma_f32_16x16x32_bf16 v[92:95], v[132:135], v[208:211], v[92:95]
	v_mfma_f32_16x16x32_bf16 v[88:91], v[140:143], v[208:211], v[88:91]
	v_mfma_f32_16x16x32_bf16 v[76:79], v[132:135], v[216:219], v[76:79]
	v_mfma_f32_16x16x32_bf16 v[72:75], v[140:143], v[216:219], v[72:75]
	v_mfma_f32_16x16x32_bf16 v[124:127], v[136:139], v[184:187], v[124:127]
	v_mfma_f32_16x16x32_bf16 v[120:123], v[144:147], v[184:187], v[120:123]
	v_mfma_f32_16x16x32_bf16 v[108:111], v[136:139], v[204:207], v[108:111]
	v_mfma_f32_16x16x32_bf16 v[104:107], v[144:147], v[204:207], v[104:107]
	v_mfma_f32_16x16x32_bf16 v[92:95], v[136:139], v[212:215], v[92:95]
	v_mfma_f32_16x16x32_bf16 v[88:91], v[144:147], v[212:215], v[88:91]
	v_mfma_f32_16x16x32_bf16 v[76:79], v[136:139], v[220:223], v[76:79]
	v_mfma_f32_16x16x32_bf16 v[72:75], v[144:147], v[220:223], v[72:75]
	v_mfma_f32_16x16x32_bf16 v[116:119], v[160:163], v[180:183], v[116:119]
	v_mfma_f32_16x16x32_bf16 v[112:115], v[168:171], v[180:183], v[112:115]
	v_mfma_f32_16x16x32_bf16 v[100:103], v[160:163], v[188:191], v[100:103]
	v_mfma_f32_16x16x32_bf16 v[96:99], v[168:171], v[188:191], v[96:99]
	v_mfma_f32_16x16x32_bf16 v[84:87], v[160:163], v[208:211], v[84:87]
	v_mfma_f32_16x16x32_bf16 v[80:83], v[168:171], v[208:211], v[80:83]
	v_mfma_f32_16x16x32_bf16 v[68:71], v[160:163], v[216:219], v[68:71]
	v_mfma_f32_16x16x32_bf16 v[64:67], v[168:171], v[216:219], v[64:67]
	v_mfma_f32_16x16x32_bf16 v[116:119], v[164:167], v[184:187], v[116:119]
	v_mfma_f32_16x16x32_bf16 v[112:115], v[176:179], v[184:187], v[112:115]
	v_mfma_f32_16x16x32_bf16 v[100:103], v[164:167], v[204:207], v[100:103]
	v_mfma_f32_16x16x32_bf16 v[96:99], v[176:179], v[204:207], v[96:99]
	s_setprio 3
	s_barrier
; #define PG8_STAGE(bufoff, gbase, voff) do { _Pragma("unroll") for (int _i = 0; _i < 2; ++_i) \
;         __builtin_amdgcn_global_load_lds((const unsigned*)((const char*)(gbase) + (voff)[_i]), (PG8_LAS unsigned*)(lds + (bufoff) + ldsw + _i * 8192), 16, 0, 0); } while (0)
; #define PG8_LDA(dst, b, h) do { _Pragma("unroll") for (int m = 0; m < 4; ++m) _Pragma("unroll") for (int k = 0; k < 2; ++k) dst[m][k] = *(const PG8_LAS bf16x8*)(lds + PG8_SA(b, h) + aoff + m * 2048 + k * 1024); } while (0)
; #define PG8_MMA(ai, bj, At, Bt) do { __builtin_amdgcn_s_setprio(1); _Pragma("unroll") for (int m = 0; m < 4; ++m) _Pragma("unroll") for (int n = 0; n < 2; ++n) _Pragma("unroll") for (int k = 0; k < 2; ++k) \
;         acc[ai][bj][m][n] = __builtin_amdgcn_mfma_f32_16x16x32_bf16(Bt[n][k], At[m][k], acc[ai][bj][m][n], 0, 0, 0); __builtin_amdgcn_s_setprio(0); } while (0)
; #define PG8_WAIT_V(n) asm volatile("s_waitcnt vmcnt(" #n ")" ::: "memory")
; #define PG8_WAIT_L(n) asm volatile("s_waitcnt lgkmcnt(" #n ")" ::: "memory")
; #define PG8_BAR __builtin_amdgcn_s_barrier()
; #define PG8_SCHED __builtin_amdgcn_sched_barrier(0)
; template <class Epi, class Sched, bool ALIGN_EPI = false, bool SP2 = false>
; __device__ __forceinline__ void gemm_phase(PG8_LAS unsigned char* lds, const Gemm g, const Sched& S, const Epi& E) {
;     ...
;         for (int t = 0; t < nt; t += 2) {
;     ...
;             PG8_STAGE(PG8_SB(1, 0), b3, voffB); PG8_STAGE(PG8_SB(1, 1), b3 + hstep, voffB); PG8_STAGE(PG8_SA(1, 0), a3, voffA); PG8_SCHED; PG8_LDA(At, 1, 1);
;             PG8_WAIT_V(8); PG8_WAIT_L(0); PG8_BAR; PG8_MMA(1, 0, At, B0); PG8_MMA(1, 1, At, B1); PG8_BAR; PG8_SCHED;
	v_mfma_f32_16x16x32_bf16 v[84:87], v[164:167], v[212:215], v[84:87]
	v_mfma_f32_16x16x32_bf16 v[80:83], v[176:179], v[212:215], v[80:83]
	v_mfma_f32_16x16x32_bf16 v[68:71], v[164:167], v[220:223], v[68:71]
	v_mfma_f32_16x16x32_bf16 v[64:67], v[176:179], v[220:223], v[64:67]
	s_setprio 0
	ds_read_b128 v[180:183], v175 offset:49152
	ds_read_b128 v[184:187], v175 offset:50176
	ds_read_b128 v[188:191], v175 offset:51200
	ds_read_b128 v[204:207], v175 offset:52224
	ds_read_b128 v[208:211], v175 offset:53248
	ds_read_b128 v[212:215], v175 offset:54272
	ds_read_b128 v[216:219], v175 offset:55296
	ds_read_b128 v[220:223], v175 offset:56320
	s_add_u32 s100, s28, 0x80
	s_addc_u32 s101, s29, 0
	s_add_u32 s28, s28, 0x40080
	s_addc_u32 s29, s29, 0
	s_add_u32 s98, s98, 0x80
	s_addc_u32 s99, s99, 0
	s_add_i32 m0, s30, s35
	s_nop 0
	global_load_lds_dwordx4 v150, s[100:101]
	s_add_i32 m0, m0, 0x2000
	s_nop 0
	global_load_lds_dwordx4 v154, s[100:101]
	s_add_i32 m0, s31, s35
	s_nop 0
	global_load_lds_dwordx4 v150, s[28:29]
	s_add_i32 m0, m0, 0x2000
	s_nop 0
	global_load_lds_dwordx4 v154, s[28:29]
	s_mov_b32 m0, s52
	s_nop 0
	global_load_lds_dwordx4 v148, s[98:99]
	s_mov_b32 m0, s53
	s_nop 0
	global_load_lds_dwordx4 v152, s[98:99]
	s_waitcnt vmcnt(8)
	s_waitcnt lgkmcnt(0)
	s_setprio 2
	s_barrier
	v_mfma_f32_16x16x32_bf16 v[60:63], v[132:135], v[180:183], v[60:63]
	v_mfma_f32_16x16x32_bf16 v[56:59], v[140:143], v[180:183], v[56:59]
	v_mfma_f32_16x16x32_bf16 v[44:47], v[132:135], v[188:191], v[44:47]
	v_mfma_f32_16x16x32_bf16 v[40:43], v[140:143], v[188:191], v[40:43]
	v_mfma_f32_16x16x32_bf16 v[28:31], v[132:135], v[208:211], v[28:31]
	v_mfma_f32_16x16x32_bf16 v[24:27], v[140:143], v[208:211], v[24:27]
	v_mfma_f32_16x16x32_bf16 v[12:15], v[132:135], v[216:219], v[12:15]
	v_mfma_f32_16x16x32_bf16 v[8:11], v[140:143], v[216:219], v[8:11]
	v_mfma_f32_16x16x32_bf16 v[60:63], v[136:139], v[184:187], v[60:63]
	v_mfma_f32_16x16x32_bf16 v[56:59], v[144:147], v[184:187], v[56:59]
	v_mfma_f32_16x16x32_bf16 v[44:47], v[136:139], v[204:207], v[44:47]
	v_mfma_f32_16x16x32_bf16 v[40:43], v[144:147], v[204:207], v[40:43]
	v_mfma_f32_16x16x32_bf16 v[28:31], v[136:139], v[212:215], v[28:31]
	v_mfma_f32_16x16x32_bf16 v[24:27], v[144:147], v[212:215], v[24:27]
	v_mfma_f32_16x16x32_bf16 v[12:15], v[136:139], v[220:223], v[12:15]
	v_mfma_f32_16x16x32_bf16 v[8:11], v[144:147], v[220:223], v[8:11]
	v_mfma_f32_16x16x32_bf16 v[52:55], v[160:163], v[180:183], v[52:55]
	v_mfma_f32_16x16x32_bf16 v[48:51], v[168:171], v[180:183], v[48:51]
	v_mfma_f32_16x16x32_bf16 v[36:39], v[160:163], v[188:191], v[36:39]
	v_mfma_f32_16x16x32_bf16 v[32:35], v[168:171], v[188:191], v[32:35]
	v_mfma_f32_16x16x32_bf16 v[20:23], v[160:163], v[208:211], v[20:23]
	v_mfma_f32_16x16x32_bf16 v[16:19], v[168:171], v[208:211], v[16:19]
	v_mfma_f32_16x16x32_bf16 v[4:7], v[160:163], v[216:219], v[4:7]
	v_mfma_f32_16x16x32_bf16 v[0:3], v[168:171], v[216:219], v[0:3]
	v_mfma_f32_16x16x32_bf16 v[52:55], v[164:167], v[184:187], v[52:55]
	v_mfma_f32_16x16x32_bf16 v[48:51], v[176:179], v[184:187], v[48:51]
	v_mfma_f32_16x16x32_bf16 v[36:39], v[164:167], v[204:207], v[36:39]
	v_mfma_f32_16x16x32_bf16 v[32:35], v[176:179], v[204:207], v[32:35]
	s_setprio 3
	s_barrier
	v_mfma_f32_16x16x32_bf16 v[20:23], v[164:167], v[212:215], v[20:23]
	v_mfma_f32_16x16x32_bf16 v[16:19], v[176:179], v[212:215], v[16:19]
	v_mfma_f32_16x16x32_bf16 v[4:7], v[164:167], v[220:223], v[4:7]
	v_mfma_f32_16x16x32_bf16 v[0:3], v[176:179], v[220:223], v[0:3]
	s_setprio 0
	s_add_i32 s59, s59, 2
	s_add_u32 vcc_lo, vcc_lo, 0x100
	s_addc_u32 vcc_hi, vcc_hi, 0
	s_cmp_gt_u32 s59, 13
	s_cbranch_scc0 .LBB0_1133
	s_and_b64 vcc, exec, s[14:15]
	s_cbranch_vccz .LBB0_1136
	s_barrier
